# + m11: in-proj log-forget-gate epilogue loads the 4 lower-bound vectors once per tile (was 32 loads with 16 full vmcnt(0) waits behind stores), layer-1 path
# speedup vs baseline: 1.0052x; 1.0052x over previous
; __device__ __forceinline__ float sigm(float x) { return __builtin_amdgcn_rcpf(1.f + __builtin_amdgcn_exp2f(-1.44269504089f * x)); }
; __device__ __forceinline__ unsigned f2h(float x) { _Float16 h = (_Float16)x; return (unsigned)__builtin_bit_cast(unsigned short, h); }
;     template <int KIND> __device__ __forceinline__ void seg(unsigned char* w, size_t dst, int ld, int cbase, const float* lb, const pg8::f32x4 (&acc)[2][2][4][2], const pg8::Unit& u, int wr, int wc, int fr, int fq) const {
;     ...
;                         const f32x4 l0 = *(const f32x4*)(lb + c), l1 = *(const f32x4*)(lb + c + 4);
;                         float r[8];
;                         if (lb0) {
; #pragma unroll
;                             for (int i = 0; i < 4; ++i) {
;                                 r[i] = fmaxf(-__log2f(1.f + __builtin_amdgcn_exp2f(-1.44269504089f * lo[i])), -126.f);
;                                 r[4 + i] = fmaxf(-__log2f(1.f + __builtin_amdgcn_exp2f(-1.44269504089f * hi[i])), -126.f);
;                             }
;                         } else {
; #pragma unroll
;                         for (int i = 0; i < 4; ++i) {
;                             const float f0 = l0[i] + (1.f - l0[i]) * sigm(lo[i]); r[i] = __log2f(fmaxf(f0, 1.17549435e-38f));
;                             const float f1 = l1[i] + (1.f - l1[i]) * sigm(hi[i]); r[4 + i] = __log2f(fmaxf(f1, 1.17549435e-38f));
;                         }
;                         }
;                         u32x4 v; v.x = f2h(r[0]) | (f2h(r[1]) << 16); v.y = f2h(r[2]) | (f2h(r[3]) << 16); v.z = f2h(r[4]) | (f2h(r[5]) << 16); v.w = f2h(r[6]) | (f2h(r[7]) << 16);
;                         *(u32x4*)((unsigned short*)(w + dst) + (size_t)row * ld + c) = v;
.LBB0_517:
	s_lshl_b32 s0, s15, 5
	v_lshl_or_b32 v132, v187, 3, s0
	v_or_b32_e32 v140, 0xfffff800, v132
	s_lshl_b32 s44, s22, 8
	v_add_u32_e32 v132, s44, v140
	v_ashrrev_i32_e32 v133, 31, v132
	s_andn2_b64 vcc, exec, s[52:53]
	v_lshl_add_u64 v[134:135], v[132:133], 2, s[58:59]
	s_cbranch_vccnz .LBB0_519
	flat_load_dwordx4 v[168:171], v[134:135] offset:16
	flat_load_dwordx4 v[164:167], v[134:135]
	flat_load_dwordx4 v[176:179], v[134:135] offset:528
	flat_load_dwordx4 v[172:175], v[134:135] offset:512
	v_mul_f32_e32 v142, 0xbfb8aa3b, v124
	v_exp_f32_e32 v142, v142
	s_waitcnt vmcnt(0) lgkmcnt(0)
	v_mov_b64_e32 v[128:129], v[168:169]
	v_mov_b64_e32 v[130:131], v[170:171]
	v_mov_b64_e32 v[136:137], v[164:165]
	v_mov_b64_e32 v[138:139], v[166:167]
	v_sub_f32_e32 v141, 1.0, v136
	v_add_f32_e32 v142, 1.0, v142
	v_rcp_f32_e32 v142, v142
	s_nop 0
	v_fma_f32 v136, v142, v141, v136
	v_mul_f32_e32 v142, 0xbfb8aa3b, v120
	v_exp_f32_e32 v142, v142
	v_sub_f32_e32 v141, 1.0, v128
	v_max_f32_e32 v136, 0x800000, v136
	v_log_f32_e32 v136, v136
	v_add_f32_e32 v142, 1.0, v142
	v_rcp_f32_e32 v142, v142
	s_nop 0
	v_fma_f32 v128, v142, v141, v128
	v_mul_f32_e32 v142, 0xbfb8aa3b, v125
	v_exp_f32_e32 v142, v142
	v_sub_f32_e32 v141, 1.0, v137
	v_max_f32_e32 v128, 0x800000, v128
	v_log_f32_e32 v128, v128
	v_add_f32_e32 v142, 1.0, v142
	v_rcp_f32_e32 v142, v142
	s_nop 0
	v_fma_f32 v137, v142, v141, v137
	v_mul_f32_e32 v142, 0xbfb8aa3b, v121
	v_exp_f32_e32 v142, v142
	v_sub_f32_e32 v141, 1.0, v129
	v_max_f32_e32 v137, 0x800000, v137
	v_log_f32_e32 v137, v137
	v_add_f32_e32 v142, 1.0, v142
	v_rcp_f32_e32 v142, v142
	s_nop 0
	v_fma_f32 v129, v142, v141, v129
	v_mul_f32_e32 v142, 0xbfb8aa3b, v126
	v_exp_f32_e32 v142, v142
	v_sub_f32_e32 v141, 1.0, v138
	v_max_f32_e32 v129, 0x800000, v129
	v_log_f32_e32 v129, v129
	v_add_f32_e32 v142, 1.0, v142
	v_rcp_f32_e32 v142, v142
	s_nop 0
	v_fma_f32 v138, v142, v141, v138
	v_mul_f32_e32 v142, 0xbfb8aa3b, v122
	v_exp_f32_e32 v142, v142
	v_max_f32_e32 v138, 0x800000, v138
	v_log_f32_e32 v141, v138
	v_sub_f32_e32 v138, 1.0, v130
	v_add_f32_e32 v142, 1.0, v142
	v_rcp_f32_e32 v142, v142
	s_nop 0
	v_fma_f32 v130, v142, v138, v130
	v_mul_f32_e32 v142, 0xbfb8aa3b, v127
	v_exp_f32_e32 v142, v142
	v_sub_f32_e32 v138, 1.0, v139
	v_max_f32_e32 v130, 0x800000, v130
	v_log_f32_e32 v130, v130
	v_add_f32_e32 v142, 1.0, v142
	v_rcp_f32_e32 v142, v142
	s_nop 0
	v_fmac_f32_e32 v139, v142, v138
	v_max_f32_e32 v138, 0x800000, v139
	v_mul_f32_e32 v139, 0xbfb8aa3b, v123
	v_exp_f32_e32 v139, v139
	v_log_f32_e32 v145, v138
	v_sub_f32_e32 v138, 1.0, v131
	v_add_f32_e32 v139, 1.0, v139
	v_rcp_f32_e32 v139, v139
	s_nop 0
	v_fmac_f32_e32 v131, v139, v138
	v_max_f32_e32 v131, 0x800000, v131
	v_log_f32_e32 v131, v131

; __device__ __forceinline__ float sigm(float x) { return __builtin_amdgcn_rcpf(1.f + __builtin_amdgcn_exp2f(-1.44269504089f * x)); }
; __device__ __forceinline__ unsigned f2h(float x) { _Float16 h = (_Float16)x; return (unsigned)__builtin_bit_cast(unsigned short, h); }
;     template <int KIND> __device__ __forceinline__ void seg(unsigned char* w, size_t dst, int ld, int cbase, const float* lb, const pg8::f32x4 (&acc)[2][2][4][2], const pg8::Unit& u, int wr, int wc, int fr, int fq) const {
;     ...
;                         const f32x4 l0 = *(const f32x4*)(lb + c), l1 = *(const f32x4*)(lb + c + 4);
;                         float r[8];
;                         if (lb0) {
; #pragma unroll
;                             for (int i = 0; i < 4; ++i) {
;                                 r[i] = fmaxf(-__log2f(1.f + __builtin_amdgcn_exp2f(-1.44269504089f * lo[i])), -126.f);
;                                 r[4 + i] = fmaxf(-__log2f(1.f + __builtin_amdgcn_exp2f(-1.44269504089f * hi[i])), -126.f);
;                             }
;                         } else {
; #pragma unroll
;                         for (int i = 0; i < 4; ++i) {
;                             const float f0 = l0[i] + (1.f - l0[i]) * sigm(lo[i]); r[i] = __log2f(fmaxf(f0, 1.17549435e-38f));
;                             const float f1 = l1[i] + (1.f - l1[i]) * sigm(hi[i]); r[4 + i] = __log2f(fmaxf(f1, 1.17549435e-38f));
;                         }
;                         }
;                         u32x4 v; v.x = f2h(r[0]) | (f2h(r[1]) << 16); v.y = f2h(r[2]) | (f2h(r[3]) << 16); v.z = f2h(r[4]) | (f2h(r[5]) << 16); v.w = f2h(r[6]) | (f2h(r[7]) << 16);
;                         *(u32x4*)((unsigned short*)(w + dst) + (size_t)row * ld + c) = v;
.LBB0_521:
	v_add_u32_e32 v136, 0x80, v132
	v_ashrrev_i32_e32 v137, 31, v136
	s_andn2_b64 vcc, exec, s[52:53]
	v_lshl_add_u64 v[136:137], v[136:137], 2, s[58:59]
	s_cbranch_vccnz .LBB0_523
	s_nop 1
	v_mov_b64_e32 v[128:129], v[176:177]
	v_mov_b64_e32 v[130:131], v[178:179]
	v_mov_b64_e32 v[146:147], v[172:173]
	v_mov_b64_e32 v[148:149], v[174:175]
	v_mul_f32_e32 v141, 0xbfb8aa3b, v116
	v_exp_f32_e32 v141, v141
	v_mul_f32_e32 v145, 0xbfb8aa3b, v112
	v_exp_f32_e32 v145, v145
	v_add_f32_e32 v141, 1.0, v141
	v_rcp_f32_e32 v141, v141
	v_add_f32_e32 v145, 1.0, v145
	v_rcp_f32_e32 v145, v145
	v_sub_f32_e32 v139, 1.0, v146
	v_fma_f32 v139, v141, v139, v146
	v_sub_f32_e32 v141, 1.0, v128
	v_fma_f32 v128, v145, v141, v128
	v_mul_f32_e32 v145, 0xbfb8aa3b, v117
	v_exp_f32_e32 v145, v145
	v_mul_f32_e32 v146, 0xbfb8aa3b, v113
	v_exp_f32_e32 v146, v146
	v_sub_f32_e32 v141, 1.0, v147
	v_add_f32_e32 v145, 1.0, v145
	v_rcp_f32_e32 v145, v145
	v_add_f32_e32 v146, 1.0, v146
	v_rcp_f32_e32 v146, v146
	v_max_f32_e32 v139, 0x800000, v139
	v_fma_f32 v141, v145, v141, v147
	v_sub_f32_e32 v145, 1.0, v129
	v_fma_f32 v129, v146, v145, v129
	v_mul_f32_e32 v146, 0xbfb8aa3b, v118
	v_exp_f32_e32 v146, v146
	v_mul_f32_e32 v147, 0xbfb8aa3b, v114
	v_exp_f32_e32 v147, v147
	v_sub_f32_e32 v145, 1.0, v148
	v_add_f32_e32 v146, 1.0, v146
	v_rcp_f32_e32 v146, v146
	v_add_f32_e32 v147, 1.0, v147
	v_rcp_f32_e32 v147, v147
	v_max_f32_e32 v128, 0x800000, v128
	v_fma_f32 v145, v146, v145, v148
	v_sub_f32_e32 v146, 1.0, v130
	v_fma_f32 v130, v147, v146, v130
	v_mul_f32_e32 v147, 0xbfb8aa3b, v119
	v_exp_f32_e32 v147, v147
	v_mul_f32_e32 v148, 0xbfb8aa3b, v115
	v_exp_f32_e32 v148, v148
	v_sub_f32_e32 v146, 1.0, v149
	v_add_f32_e32 v147, 1.0, v147
	v_rcp_f32_e32 v147, v147
	v_add_f32_e32 v148, 1.0, v148
	v_rcp_f32_e32 v148, v148
	v_max_f32_e32 v141, 0x800000, v141
	v_fmac_f32_e32 v149, v147, v146
	v_sub_f32_e32 v147, 1.0, v131
	v_fmac_f32_e32 v131, v148, v147
	v_max_f32_e32 v129, 0x800000, v129
	v_max_f32_e32 v145, 0x800000, v145
	v_max_f32_e32 v130, 0x800000, v130
	v_max_f32_e32 v146, 0x800000, v149
	v_max_f32_e32 v131, 0x800000, v131
	v_log_f32_e32 v139, v139
	v_log_f32_e32 v128, v128
	v_log_f32_e32 v141, v141
	v_log_f32_e32 v129, v129
	v_log_f32_e32 v145, v145
	v_log_f32_e32 v130, v130
	v_log_f32_e32 v146, v146
	v_log_f32_e32 v131, v131

; __device__ __forceinline__ float sigm(float x) { return __builtin_amdgcn_rcpf(1.f + __builtin_amdgcn_exp2f(-1.44269504089f * x)); }
; __device__ __forceinline__ unsigned f2h(float x) { _Float16 h = (_Float16)x; return (unsigned)__builtin_bit_cast(unsigned short, h); }
;     template <int KIND> __device__ __forceinline__ void seg(unsigned char* w, size_t dst, int ld, int cbase, const float* lb, const pg8::f32x4 (&acc)[2][2][4][2], const pg8::Unit& u, int wr, int wc, int fr, int fq) const {
;     ...
;                         const f32x4 l0 = *(const f32x4*)(lb + c), l1 = *(const f32x4*)(lb + c + 4);
;                         float r[8];
;                         if (lb0) {
; #pragma unroll
;                             for (int i = 0; i < 4; ++i) {
;                                 r[i] = fmaxf(-__log2f(1.f + __builtin_amdgcn_exp2f(-1.44269504089f * lo[i])), -126.f);
;                                 r[4 + i] = fmaxf(-__log2f(1.f + __builtin_amdgcn_exp2f(-1.44269504089f * hi[i])), -126.f);
;                             }
;                         } else {
; #pragma unroll
;                         for (int i = 0; i < 4; ++i) {
;                             const float f0 = l0[i] + (1.f - l0[i]) * sigm(lo[i]); r[i] = __log2f(fmaxf(f0, 1.17549435e-38f));
;                             const float f1 = l1[i] + (1.f - l1[i]) * sigm(hi[i]); r[4 + i] = __log2f(fmaxf(f1, 1.17549435e-38f));
;                         }
;                         }
;                         u32x4 v; v.x = f2h(r[0]) | (f2h(r[1]) << 16); v.y = f2h(r[2]) | (f2h(r[3]) << 16); v.z = f2h(r[4]) | (f2h(r[5]) << 16); v.w = f2h(r[6]) | (f2h(r[7]) << 16);
;                         *(u32x4*)((unsigned short*)(w + dst) + (size_t)row * ld + c) = v;
.LBB0_525:
	s_andn2_b64 vcc, exec, s[44:45]
	s_cbranch_vccnz .LBB0_527
	s_nop 1
	v_mov_b64_e32 v[128:129], v[168:169]
	v_mov_b64_e32 v[130:131], v[170:171]
	v_mov_b64_e32 v[146:147], v[164:165]
	v_mov_b64_e32 v[148:149], v[166:167]
	v_mul_f32_e32 v142, 0xbfb8aa3b, v108
	v_exp_f32_e32 v142, v142
	v_mul_f32_e32 v143, 0xbfb8aa3b, v104
	v_exp_f32_e32 v143, v143
	v_add_f32_e32 v142, 1.0, v142
	v_rcp_f32_e32 v142, v142
	v_add_f32_e32 v143, 1.0, v143
	v_rcp_f32_e32 v143, v143
	v_sub_f32_e32 v139, 1.0, v146
	v_fma_f32 v139, v142, v139, v146
	v_sub_f32_e32 v142, 1.0, v128
	v_fma_f32 v128, v143, v142, v128
	v_mul_f32_e32 v143, 0xbfb8aa3b, v109
	v_exp_f32_e32 v143, v143
	v_sub_f32_e32 v142, 1.0, v147
	v_max_f32_e32 v139, 0x800000, v139
	v_max_f32_e32 v128, 0x800000, v128
	v_add_f32_e32 v143, 1.0, v143
	v_rcp_f32_e32 v143, v143
	v_log_f32_e32 v139, v139
	v_log_f32_e32 v128, v128
	v_fma_f32 v142, v143, v142, v147
	v_mul_f32_e32 v143, 0xbfb8aa3b, v105
	v_exp_f32_e32 v143, v143
	v_max_f32_e32 v142, 0x800000, v142
	v_log_f32_e32 v145, v142
	v_sub_f32_e32 v142, 1.0, v129
	v_add_f32_e32 v143, 1.0, v143
	v_rcp_f32_e32 v143, v143
	s_nop 0
	v_fma_f32 v129, v143, v142, v129
	v_mul_f32_e32 v143, 0xbfb8aa3b, v110
	v_exp_f32_e32 v143, v143
	v_sub_f32_e32 v142, 1.0, v148
	v_max_f32_e32 v129, 0x800000, v129
	v_log_f32_e32 v129, v129
	v_add_f32_e32 v143, 1.0, v143
	v_rcp_f32_e32 v143, v143
	s_nop 0
	v_fma_f32 v142, v143, v142, v148
	v_mul_f32_e32 v143, 0xbfb8aa3b, v106
	v_exp_f32_e32 v143, v143
	v_max_f32_e32 v142, 0x800000, v142
	v_log_f32_e32 v146, v142
	v_sub_f32_e32 v142, 1.0, v130
	v_add_f32_e32 v143, 1.0, v143
	v_rcp_f32_e32 v143, v143
	s_nop 0
	v_fma_f32 v130, v143, v142, v130
	v_mul_f32_e32 v143, 0xbfb8aa3b, v111
	v_exp_f32_e32 v143, v143
	v_sub_f32_e32 v142, 1.0, v149
	v_max_f32_e32 v130, 0x800000, v130
	v_log_f32_e32 v130, v130
	v_add_f32_e32 v143, 1.0, v143
	v_rcp_f32_e32 v143, v143
	s_nop 0
	v_fmac_f32_e32 v149, v143, v142
	v_mul_f32_e32 v143, 0xbfb8aa3b, v107
	v_exp_f32_e32 v143, v143
	v_max_f32_e32 v142, 0x800000, v149
	v_log_f32_e32 v147, v142
	v_sub_f32_e32 v142, 1.0, v131
	v_add_f32_e32 v143, 1.0, v143
	v_rcp_f32_e32 v143, v143
	s_nop 0
	v_fmac_f32_e32 v131, v143, v142
	v_max_f32_e32 v131, 0x800000, v131
	v_log_f32_e32 v131, v131

; __device__ __forceinline__ float sigm(float x) { return __builtin_amdgcn_rcpf(1.f + __builtin_amdgcn_exp2f(-1.44269504089f * x)); }
; __device__ __forceinline__ unsigned f2h(float x) { _Float16 h = (_Float16)x; return (unsigned)__builtin_bit_cast(unsigned short, h); }
;     template <int KIND> __device__ __forceinline__ void seg(unsigned char* w, size_t dst, int ld, int cbase, const float* lb, const pg8::f32x4 (&acc)[2][2][4][2], const pg8::Unit& u, int wr, int wc, int fr, int fq) const {
;     ...
;                         const f32x4 l0 = *(const f32x4*)(lb + c), l1 = *(const f32x4*)(lb + c + 4);
;                         float r[8];
;                         if (lb0) {
; #pragma unroll
;                             for (int i = 0; i < 4; ++i) {
;                                 r[i] = fmaxf(-__log2f(1.f + __builtin_amdgcn_exp2f(-1.44269504089f * lo[i])), -126.f);
;                                 r[4 + i] = fmaxf(-__log2f(1.f + __builtin_amdgcn_exp2f(-1.44269504089f * hi[i])), -126.f);
;                             }
;                         } else {
; #pragma unroll
;                         for (int i = 0; i < 4; ++i) {
;                             const float f0 = l0[i] + (1.f - l0[i]) * sigm(lo[i]); r[i] = __log2f(fmaxf(f0, 1.17549435e-38f));
;                             const float f1 = l1[i] + (1.f - l1[i]) * sigm(hi[i]); r[4 + i] = __log2f(fmaxf(f1, 1.17549435e-38f));
;                         }
;                         }
;                         u32x4 v; v.x = f2h(r[0]) | (f2h(r[1]) << 16); v.y = f2h(r[2]) | (f2h(r[3]) << 16); v.z = f2h(r[4]) | (f2h(r[5]) << 16); v.w = f2h(r[6]) | (f2h(r[7]) << 16);
;                         *(u32x4*)((unsigned short*)(w + dst) + (size_t)row * ld + c) = v;
.LBB0_529:
	s_andn2_b64 vcc, exec, s[44:45]
	s_cbranch_vccnz .LBB0_531
	s_nop 1
	v_mov_b64_e32 v[128:129], v[176:177]
	v_mov_b64_e32 v[130:131], v[178:179]
	v_mov_b64_e32 v[146:147], v[172:173]
	v_mov_b64_e32 v[148:149], v[174:175]
	v_mul_f32_e32 v145, 0xbfb8aa3b, v100
	v_exp_f32_e32 v145, v145
	v_sub_f32_e32 v139, 1.0, v146
	v_add_f32_e32 v145, 1.0, v145
	v_rcp_f32_e32 v145, v145
	s_nop 0
	v_fma_f32 v139, v145, v139, v146
	v_mul_f32_e32 v146, 0xbfb8aa3b, v96
	v_exp_f32_e32 v146, v146
	v_sub_f32_e32 v145, 1.0, v128
	v_max_f32_e32 v139, 0x800000, v139
	v_log_f32_e32 v139, v139
	v_add_f32_e32 v146, 1.0, v146
	v_rcp_f32_e32 v146, v146
	s_nop 0
	v_fma_f32 v128, v146, v145, v128
	v_mul_f32_e32 v146, 0xbfb8aa3b, v101
	v_exp_f32_e32 v146, v146
	v_sub_f32_e32 v145, 1.0, v147
	v_max_f32_e32 v128, 0x800000, v128
	v_log_f32_e32 v128, v128
	v_add_f32_e32 v146, 1.0, v146
	v_rcp_f32_e32 v146, v146
	s_nop 0
	v_fma_f32 v145, v146, v145, v147
	v_mul_f32_e32 v147, 0xbfb8aa3b, v97
	v_exp_f32_e32 v147, v147
	v_sub_f32_e32 v146, 1.0, v129
	v_max_f32_e32 v145, 0x800000, v145
	v_log_f32_e32 v145, v145
	v_add_f32_e32 v147, 1.0, v147
	v_rcp_f32_e32 v147, v147
	s_nop 0
	v_fma_f32 v129, v147, v146, v129
	v_mul_f32_e32 v147, 0xbfb8aa3b, v102
	v_exp_f32_e32 v147, v147
	v_sub_f32_e32 v146, 1.0, v148
	v_max_f32_e32 v129, 0x800000, v129
	v_log_f32_e32 v129, v129
	v_add_f32_e32 v147, 1.0, v147
	v_rcp_f32_e32 v147, v147
	s_nop 0
	v_fma_f32 v146, v147, v146, v148
	v_mul_f32_e32 v148, 0xbfb8aa3b, v98
	v_exp_f32_e32 v148, v148
	v_sub_f32_e32 v147, 1.0, v130
	v_max_f32_e32 v146, 0x800000, v146
	v_log_f32_e32 v146, v146
	v_add_f32_e32 v148, 1.0, v148
	v_rcp_f32_e32 v148, v148
	s_nop 0
	v_fma_f32 v130, v148, v147, v130
	v_mul_f32_e32 v148, 0xbfb8aa3b, v103
	v_exp_f32_e32 v148, v148
	v_sub_f32_e32 v147, 1.0, v149
	v_max_f32_e32 v130, 0x800000, v130
	v_log_f32_e32 v130, v130
	v_add_f32_e32 v148, 1.0, v148
	v_rcp_f32_e32 v148, v148
	s_nop 0
	v_fmac_f32_e32 v149, v148, v147
	v_max_f32_e32 v147, 0x800000, v149
	v_mul_f32_e32 v149, 0xbfb8aa3b, v99
	v_exp_f32_e32 v149, v149
	v_sub_f32_e32 v148, 1.0, v131
	v_log_f32_e32 v147, v147
	v_add_f32_e32 v149, 1.0, v149
	v_rcp_f32_e32 v149, v149
	s_nop 0
	v_fmac_f32_e32 v131, v149, v148
	v_max_f32_e32 v131, 0x800000, v131
	v_log_f32_e32 v131, v131

; __device__ __forceinline__ float sigm(float x) { return __builtin_amdgcn_rcpf(1.f + __builtin_amdgcn_exp2f(-1.44269504089f * x)); }
; __device__ __forceinline__ unsigned f2h(float x) { _Float16 h = (_Float16)x; return (unsigned)__builtin_bit_cast(unsigned short, h); }
;     template <int KIND> __device__ __forceinline__ void seg(unsigned char* w, size_t dst, int ld, int cbase, const float* lb, const pg8::f32x4 (&acc)[2][2][4][2], const pg8::Unit& u, int wr, int wc, int fr, int fq) const {
;     ...
;                         const f32x4 l0 = *(const f32x4*)(lb + c), l1 = *(const f32x4*)(lb + c + 4);
;                         float r[8];
;                         if (lb0) {
; #pragma unroll
;                             for (int i = 0; i < 4; ++i) {
;                                 r[i] = fmaxf(-__log2f(1.f + __builtin_amdgcn_exp2f(-1.44269504089f * lo[i])), -126.f);
;                                 r[4 + i] = fmaxf(-__log2f(1.f + __builtin_amdgcn_exp2f(-1.44269504089f * hi[i])), -126.f);
;                             }
;                         } else {
; #pragma unroll
;                         for (int i = 0; i < 4; ++i) {
;                             const float f0 = l0[i] + (1.f - l0[i]) * sigm(lo[i]); r[i] = __log2f(fmaxf(f0, 1.17549435e-38f));
;                             const float f1 = l1[i] + (1.f - l1[i]) * sigm(hi[i]); r[4 + i] = __log2f(fmaxf(f1, 1.17549435e-38f));
;                         }
;                         }
;                         u32x4 v; v.x = f2h(r[0]) | (f2h(r[1]) << 16); v.y = f2h(r[2]) | (f2h(r[3]) << 16); v.z = f2h(r[4]) | (f2h(r[5]) << 16); v.w = f2h(r[6]) | (f2h(r[7]) << 16);
;                         *(u32x4*)((unsigned short*)(w + dst) + (size_t)row * ld + c) = v;
.LBB0_533:
	s_andn2_b64 vcc, exec, s[44:45]
	s_cbranch_vccnz .LBB0_535
	s_nop 1
	v_mov_b64_e32 v[128:129], v[168:169]
	v_mov_b64_e32 v[130:131], v[170:171]
	v_mov_b64_e32 v[146:147], v[164:165]
	v_mov_b64_e32 v[148:149], v[166:167]
	v_mul_f32_e32 v142, 0xbfb8aa3b, v92
	v_exp_f32_e32 v142, v142
	v_mul_f32_e32 v143, 0xbfb8aa3b, v88
	v_exp_f32_e32 v143, v143
	v_add_f32_e32 v142, 1.0, v142
	v_rcp_f32_e32 v142, v142
	v_add_f32_e32 v143, 1.0, v143
	v_rcp_f32_e32 v143, v143
	v_sub_f32_e32 v139, 1.0, v146
	v_fma_f32 v139, v142, v139, v146
	v_sub_f32_e32 v142, 1.0, v128
	v_fma_f32 v128, v143, v142, v128
	v_mul_f32_e32 v143, 0xbfb8aa3b, v93
	v_exp_f32_e32 v143, v143
	v_sub_f32_e32 v142, 1.0, v147
	v_max_f32_e32 v139, 0x800000, v139
	v_max_f32_e32 v128, 0x800000, v128
	v_add_f32_e32 v143, 1.0, v143
	v_rcp_f32_e32 v143, v143
	v_log_f32_e32 v139, v139
	v_log_f32_e32 v128, v128
	v_fma_f32 v142, v143, v142, v147
	v_mul_f32_e32 v143, 0xbfb8aa3b, v89
	v_exp_f32_e32 v143, v143
	v_max_f32_e32 v142, 0x800000, v142
	v_log_f32_e32 v145, v142
	v_sub_f32_e32 v142, 1.0, v129
	v_add_f32_e32 v143, 1.0, v143
	v_rcp_f32_e32 v143, v143
	s_nop 0
	v_fma_f32 v129, v143, v142, v129
	v_mul_f32_e32 v143, 0xbfb8aa3b, v94
	v_exp_f32_e32 v143, v143
	v_sub_f32_e32 v142, 1.0, v148
	v_max_f32_e32 v129, 0x800000, v129
	v_log_f32_e32 v129, v129
	v_add_f32_e32 v143, 1.0, v143
	v_rcp_f32_e32 v143, v143
	s_nop 0
	v_fma_f32 v142, v143, v142, v148
	v_mul_f32_e32 v143, 0xbfb8aa3b, v90
	v_exp_f32_e32 v143, v143
	v_max_f32_e32 v142, 0x800000, v142
	v_log_f32_e32 v146, v142
	v_sub_f32_e32 v142, 1.0, v130
	v_add_f32_e32 v143, 1.0, v143
	v_rcp_f32_e32 v143, v143
	s_nop 0
	v_fma_f32 v130, v143, v142, v130
	v_mul_f32_e32 v143, 0xbfb8aa3b, v95
	v_exp_f32_e32 v143, v143
	v_sub_f32_e32 v142, 1.0, v149
	v_max_f32_e32 v130, 0x800000, v130
	v_log_f32_e32 v130, v130
	v_add_f32_e32 v143, 1.0, v143
	v_rcp_f32_e32 v143, v143
	s_nop 0
	v_fmac_f32_e32 v149, v143, v142
	v_mul_f32_e32 v143, 0xbfb8aa3b, v91
	v_exp_f32_e32 v143, v143
	v_max_f32_e32 v142, 0x800000, v149
	v_log_f32_e32 v147, v142
	v_sub_f32_e32 v142, 1.0, v131
	v_add_f32_e32 v143, 1.0, v143
	v_rcp_f32_e32 v143, v143
	s_nop 0
	v_fmac_f32_e32 v131, v143, v142
	v_max_f32_e32 v131, 0x800000, v131
	v_log_f32_e32 v131, v131

; __device__ __forceinline__ float sigm(float x) { return __builtin_amdgcn_rcpf(1.f + __builtin_amdgcn_exp2f(-1.44269504089f * x)); }
; __device__ __forceinline__ unsigned f2h(float x) { _Float16 h = (_Float16)x; return (unsigned)__builtin_bit_cast(unsigned short, h); }
;     template <int KIND> __device__ __forceinline__ void seg(unsigned char* w, size_t dst, int ld, int cbase, const float* lb, const pg8::f32x4 (&acc)[2][2][4][2], const pg8::Unit& u, int wr, int wc, int fr, int fq) const {
;     ...
;                         const f32x4 l0 = *(const f32x4*)(lb + c), l1 = *(const f32x4*)(lb + c + 4);
;                         float r[8];
;                         if (lb0) {
; #pragma unroll
;                             for (int i = 0; i < 4; ++i) {
;                                 r[i] = fmaxf(-__log2f(1.f + __builtin_amdgcn_exp2f(-1.44269504089f * lo[i])), -126.f);
;                                 r[4 + i] = fmaxf(-__log2f(1.f + __builtin_amdgcn_exp2f(-1.44269504089f * hi[i])), -126.f);
;                             }
;                         } else {
; #pragma unroll
;                         for (int i = 0; i < 4; ++i) {
;                             const float f0 = l0[i] + (1.f - l0[i]) * sigm(lo[i]); r[i] = __log2f(fmaxf(f0, 1.17549435e-38f));
;                             const float f1 = l1[i] + (1.f - l1[i]) * sigm(hi[i]); r[4 + i] = __log2f(fmaxf(f1, 1.17549435e-38f));
;                         }
;                         }
;                         u32x4 v; v.x = f2h(r[0]) | (f2h(r[1]) << 16); v.y = f2h(r[2]) | (f2h(r[3]) << 16); v.z = f2h(r[4]) | (f2h(r[5]) << 16); v.w = f2h(r[6]) | (f2h(r[7]) << 16);
;                         *(u32x4*)((unsigned short*)(w + dst) + (size_t)row * ld + c) = v;
.LBB0_537:
	s_andn2_b64 vcc, exec, s[44:45]
	s_cbranch_vccnz .LBB0_539
	s_nop 1
	v_mov_b64_e32 v[128:129], v[176:177]
	v_mov_b64_e32 v[130:131], v[178:179]
	v_mov_b64_e32 v[146:147], v[172:173]
	v_mov_b64_e32 v[148:149], v[174:175]
	v_mul_f32_e32 v145, 0xbfb8aa3b, v84
	v_exp_f32_e32 v145, v145
	v_sub_f32_e32 v139, 1.0, v146
	v_add_f32_e32 v145, 1.0, v145
	v_rcp_f32_e32 v145, v145
	s_nop 0
	v_fma_f32 v139, v145, v139, v146
	v_mul_f32_e32 v146, 0xbfb8aa3b, v80
	v_exp_f32_e32 v146, v146
	v_sub_f32_e32 v145, 1.0, v128
	v_max_f32_e32 v139, 0x800000, v139
	v_log_f32_e32 v139, v139
	v_add_f32_e32 v146, 1.0, v146
	v_rcp_f32_e32 v146, v146
	s_nop 0
	v_fma_f32 v128, v146, v145, v128
	v_mul_f32_e32 v146, 0xbfb8aa3b, v85
	v_exp_f32_e32 v146, v146
	v_sub_f32_e32 v145, 1.0, v147
	v_max_f32_e32 v128, 0x800000, v128
	v_log_f32_e32 v128, v128
	v_add_f32_e32 v146, 1.0, v146
	v_rcp_f32_e32 v146, v146
	s_nop 0
	v_fma_f32 v145, v146, v145, v147
	v_mul_f32_e32 v147, 0xbfb8aa3b, v81
	v_exp_f32_e32 v147, v147
	v_sub_f32_e32 v146, 1.0, v129
	v_max_f32_e32 v145, 0x800000, v145
	v_log_f32_e32 v145, v145
	v_add_f32_e32 v147, 1.0, v147
	v_rcp_f32_e32 v147, v147
	s_nop 0
	v_fma_f32 v129, v147, v146, v129
	v_mul_f32_e32 v147, 0xbfb8aa3b, v86
	v_exp_f32_e32 v147, v147
	v_sub_f32_e32 v146, 1.0, v148
	v_max_f32_e32 v129, 0x800000, v129
	v_log_f32_e32 v129, v129
	v_add_f32_e32 v147, 1.0, v147
	v_rcp_f32_e32 v147, v147
	s_nop 0
	v_fma_f32 v146, v147, v146, v148
	v_mul_f32_e32 v148, 0xbfb8aa3b, v82
	v_exp_f32_e32 v148, v148
	v_sub_f32_e32 v147, 1.0, v130
	v_max_f32_e32 v146, 0x800000, v146
	v_log_f32_e32 v146, v146
	v_add_f32_e32 v148, 1.0, v148
	v_rcp_f32_e32 v148, v148
	s_nop 0
	v_fma_f32 v130, v148, v147, v130
	v_mul_f32_e32 v148, 0xbfb8aa3b, v87
	v_exp_f32_e32 v148, v148
	v_sub_f32_e32 v147, 1.0, v149
	v_max_f32_e32 v130, 0x800000, v130
	v_log_f32_e32 v130, v130
	v_add_f32_e32 v148, 1.0, v148
	v_rcp_f32_e32 v148, v148
	s_nop 0
	v_fmac_f32_e32 v149, v148, v147
	v_max_f32_e32 v147, 0x800000, v149
	v_mul_f32_e32 v149, 0xbfb8aa3b, v83
	v_exp_f32_e32 v149, v149
	v_sub_f32_e32 v148, 1.0, v131
	v_log_f32_e32 v147, v147
	v_add_f32_e32 v149, 1.0, v149
	v_rcp_f32_e32 v149, v149
	s_nop 0
	v_fmac_f32_e32 v131, v149, v148
	v_max_f32_e32 v131, 0x800000, v131
	v_log_f32_e32 v131, v131

; __device__ __forceinline__ float sigm(float x) { return __builtin_amdgcn_rcpf(1.f + __builtin_amdgcn_exp2f(-1.44269504089f * x)); }
;     template <int KIND> __device__ __forceinline__ void seg(unsigned char* w, size_t dst, int ld, int cbase, const float* lb, const pg8::f32x4 (&acc)[2][2][4][2], const pg8::Unit& u, int wr, int wc, int fr, int fq) const {
;     ...
;                         const f32x4 l0 = *(const f32x4*)(lb + c), l1 = *(const f32x4*)(lb + c + 4);
;                         float r[8];
;                         if (lb0) {
; #pragma unroll
;                             for (int i = 0; i < 4; ++i) {
;                                 r[i] = fmaxf(-__log2f(1.f + __builtin_amdgcn_exp2f(-1.44269504089f * lo[i])), -126.f);
;                                 r[4 + i] = fmaxf(-__log2f(1.f + __builtin_amdgcn_exp2f(-1.44269504089f * hi[i])), -126.f);
;                             }
;                         } else {
; #pragma unroll
;                         for (int i = 0; i < 4; ++i) {
;                             const float f0 = l0[i] + (1.f - l0[i]) * sigm(lo[i]); r[i] = __log2f(fmaxf(f0, 1.17549435e-38f));
;                             const float f1 = l1[i] + (1.f - l1[i]) * sigm(hi[i]); r[4 + i] = __log2f(fmaxf(f1, 1.17549435e-38f));
;                         }
.LBB0_541:
	s_andn2_b64 vcc, exec, s[44:45]
	s_cbranch_vccnz .LBB0_543
	s_nop 1
	v_mov_b64_e32 v[128:129], v[168:169]
	v_mov_b64_e32 v[130:131], v[170:171]
	v_mov_b64_e32 v[146:147], v[164:165]
	v_mov_b64_e32 v[148:149], v[166:167]
	v_mul_f32_e32 v142, 0xbfb8aa3b, v76
	v_exp_f32_e32 v142, v142
	v_mul_f32_e32 v143, 0xbfb8aa3b, v72
	v_exp_f32_e32 v143, v143
	v_add_f32_e32 v142, 1.0, v142
	v_rcp_f32_e32 v142, v142
	v_add_f32_e32 v143, 1.0, v143
	v_rcp_f32_e32 v143, v143
	v_sub_f32_e32 v139, 1.0, v146
	v_fma_f32 v139, v142, v139, v146
	v_sub_f32_e32 v142, 1.0, v128
	v_fma_f32 v128, v143, v142, v128
	v_mul_f32_e32 v143, 0xbfb8aa3b, v77
	v_exp_f32_e32 v143, v143
	v_sub_f32_e32 v142, 1.0, v147
	v_max_f32_e32 v139, 0x800000, v139
	v_max_f32_e32 v128, 0x800000, v128
	v_add_f32_e32 v143, 1.0, v143
	v_rcp_f32_e32 v143, v143
	v_log_f32_e32 v139, v139
	v_log_f32_e32 v128, v128
	v_fma_f32 v142, v143, v142, v147
	v_mul_f32_e32 v143, 0xbfb8aa3b, v73
	v_exp_f32_e32 v143, v143
	v_max_f32_e32 v142, 0x800000, v142
	v_log_f32_e32 v145, v142
	v_sub_f32_e32 v142, 1.0, v129
	v_add_f32_e32 v143, 1.0, v143
	v_rcp_f32_e32 v143, v143
	s_nop 0
	v_fma_f32 v129, v143, v142, v129
	v_mul_f32_e32 v143, 0xbfb8aa3b, v78
	v_exp_f32_e32 v143, v143
	v_sub_f32_e32 v142, 1.0, v148
	v_max_f32_e32 v129, 0x800000, v129
	v_log_f32_e32 v129, v129
	v_add_f32_e32 v143, 1.0, v143
	v_rcp_f32_e32 v143, v143
	s_nop 0
	v_fma_f32 v142, v143, v142, v148
	v_mul_f32_e32 v143, 0xbfb8aa3b, v74
	v_exp_f32_e32 v143, v143
	v_max_f32_e32 v142, 0x800000, v142
	v_log_f32_e32 v146, v142
	v_sub_f32_e32 v142, 1.0, v130
	v_add_f32_e32 v143, 1.0, v143
	v_rcp_f32_e32 v143, v143
	s_nop 0
	v_fma_f32 v130, v143, v142, v130
	v_mul_f32_e32 v143, 0xbfb8aa3b, v79
	v_exp_f32_e32 v143, v143
	v_sub_f32_e32 v142, 1.0, v149
	v_max_f32_e32 v130, 0x800000, v130
	v_log_f32_e32 v130, v130
	v_add_f32_e32 v143, 1.0, v143
	v_rcp_f32_e32 v143, v143
	s_nop 0
	v_fmac_f32_e32 v149, v143, v142
	v_mul_f32_e32 v143, 0xbfb8aa3b, v75
	v_exp_f32_e32 v143, v143
	v_max_f32_e32 v142, 0x800000, v149
	v_log_f32_e32 v147, v142
	v_sub_f32_e32 v142, 1.0, v131
	v_add_f32_e32 v143, 1.0, v143
	v_rcp_f32_e32 v143, v143
	s_nop 0
	v_fmac_f32_e32 v131, v143, v142
	v_max_f32_e32 v131, 0x800000, v131
	v_log_f32_e32 v131, v131

; __device__ __forceinline__ float sigm(float x) { return __builtin_amdgcn_rcpf(1.f + __builtin_amdgcn_exp2f(-1.44269504089f * x)); }
;     template <int KIND> __device__ __forceinline__ void seg(unsigned char* w, size_t dst, int ld, int cbase, const float* lb, const pg8::f32x4 (&acc)[2][2][4][2], const pg8::Unit& u, int wr, int wc, int fr, int fq) const {
;     ...
;                         const f32x4 l0 = *(const f32x4*)(lb + c), l1 = *(const f32x4*)(lb + c + 4);
;                         float r[8];
;                         if (lb0) {
; #pragma unroll
;                             for (int i = 0; i < 4; ++i) {
;                                 r[i] = fmaxf(-__log2f(1.f + __builtin_amdgcn_exp2f(-1.44269504089f * lo[i])), -126.f);
;                                 r[4 + i] = fmaxf(-__log2f(1.f + __builtin_amdgcn_exp2f(-1.44269504089f * hi[i])), -126.f);
;                             }
;                         } else {
; #pragma unroll
;                         for (int i = 0; i < 4; ++i) {
;                             const float f0 = l0[i] + (1.f - l0[i]) * sigm(lo[i]); r[i] = __log2f(fmaxf(f0, 1.17549435e-38f));
;                             const float f1 = l1[i] + (1.f - l1[i]) * sigm(hi[i]); r[4 + i] = __log2f(fmaxf(f1, 1.17549435e-38f));
;                         }
.LBB0_545:
	s_andn2_b64 vcc, exec, s[44:45]
	s_cbranch_vccnz .LBB0_547
	s_nop 1
	v_mov_b64_e32 v[128:129], v[176:177]
	v_mov_b64_e32 v[130:131], v[178:179]
	v_mov_b64_e32 v[144:145], v[172:173]
	v_mov_b64_e32 v[146:147], v[174:175]
	v_mul_f32_e32 v148, 0xbfb8aa3b, v68
	v_exp_f32_e32 v148, v148
	v_sub_f32_e32 v139, 1.0, v144
	v_add_f32_e32 v148, 1.0, v148
	v_rcp_f32_e32 v148, v148
	s_nop 0
	v_fma_f32 v139, v148, v139, v144
	v_mul_f32_e32 v148, 0xbfb8aa3b, v64
	v_exp_f32_e32 v148, v148
	v_sub_f32_e32 v144, 1.0, v128
	v_max_f32_e32 v139, 0x800000, v139
	v_log_f32_e32 v139, v139
	v_add_f32_e32 v148, 1.0, v148
	v_rcp_f32_e32 v148, v148
	s_nop 0
	v_fma_f32 v128, v148, v144, v128
	v_mul_f32_e32 v148, 0xbfb8aa3b, v69
	v_exp_f32_e32 v148, v148
	v_sub_f32_e32 v144, 1.0, v145
	v_max_f32_e32 v128, 0x800000, v128
	v_log_f32_e32 v128, v128
	v_add_f32_e32 v148, 1.0, v148
	v_rcp_f32_e32 v148, v148
	s_nop 0
	v_fma_f32 v144, v148, v144, v145
	v_mul_f32_e32 v148, 0xbfb8aa3b, v65
	v_exp_f32_e32 v148, v148
	v_sub_f32_e32 v145, 1.0, v129
	v_max_f32_e32 v144, 0x800000, v144
	v_log_f32_e32 v144, v144
	v_add_f32_e32 v148, 1.0, v148
	v_rcp_f32_e32 v148, v148
	s_nop 0
	v_fma_f32 v129, v148, v145, v129
	v_mul_f32_e32 v148, 0xbfb8aa3b, v70
	v_exp_f32_e32 v148, v148
	v_sub_f32_e32 v145, 1.0, v146
	v_max_f32_e32 v129, 0x800000, v129
	v_log_f32_e32 v129, v129
	v_add_f32_e32 v148, 1.0, v148
	v_rcp_f32_e32 v148, v148
	s_nop 0
	v_fma_f32 v145, v148, v145, v146
	v_mul_f32_e32 v148, 0xbfb8aa3b, v66
	v_exp_f32_e32 v148, v148
	v_sub_f32_e32 v146, 1.0, v130
	v_max_f32_e32 v145, 0x800000, v145
	v_log_f32_e32 v145, v145
	v_add_f32_e32 v148, 1.0, v148
	v_rcp_f32_e32 v148, v148
	s_nop 0
	v_fma_f32 v130, v148, v146, v130
	v_mul_f32_e32 v148, 0xbfb8aa3b, v71
	v_exp_f32_e32 v148, v148
	v_sub_f32_e32 v146, 1.0, v147
	v_max_f32_e32 v130, 0x800000, v130
	v_log_f32_e32 v130, v130
	v_add_f32_e32 v148, 1.0, v148
	v_rcp_f32_e32 v148, v148
	s_nop 0
	v_fmac_f32_e32 v147, v148, v146
	v_mul_f32_e32 v148, 0xbfb8aa3b, v67
	v_exp_f32_e32 v148, v148
	v_max_f32_e32 v146, 0x800000, v147
	v_sub_f32_e32 v147, 1.0, v131
	v_log_f32_e32 v146, v146
	v_add_f32_e32 v148, 1.0, v148
	v_rcp_f32_e32 v148, v148
	s_nop 0
	v_fmac_f32_e32 v131, v148, v147
	v_max_f32_e32 v131, 0x800000, v131
	v_log_f32_e32 v131, v131

; __device__ __forceinline__ float sigm(float x) { return __builtin_amdgcn_rcpf(1.f + __builtin_amdgcn_exp2f(-1.44269504089f * x)); }
;     template <int KIND> __device__ __forceinline__ void seg(unsigned char* w, size_t dst, int ld, int cbase, const float* lb, const pg8::f32x4 (&acc)[2][2][4][2], const pg8::Unit& u, int wr, int wc, int fr, int fq) const {
;     ...
;                         const f32x4 l0 = *(const f32x4*)(lb + c), l1 = *(const f32x4*)(lb + c + 4);
;                         float r[8];
;                         if (lb0) {
; #pragma unroll
;                             for (int i = 0; i < 4; ++i) {
;                                 r[i] = fmaxf(-__log2f(1.f + __builtin_amdgcn_exp2f(-1.44269504089f * lo[i])), -126.f);
;                                 r[4 + i] = fmaxf(-__log2f(1.f + __builtin_amdgcn_exp2f(-1.44269504089f * hi[i])), -126.f);
;                             }
;                         } else {
; #pragma unroll
;                         for (int i = 0; i < 4; ++i) {
;                             const float f0 = l0[i] + (1.f - l0[i]) * sigm(lo[i]); r[i] = __log2f(fmaxf(f0, 1.17549435e-38f));
;                             const float f1 = l1[i] + (1.f - l1[i]) * sigm(hi[i]); r[4 + i] = __log2f(fmaxf(f1, 1.17549435e-38f));
;                         }
.LBB0_549:
	s_andn2_b64 vcc, exec, s[44:45]
	s_cbranch_vccnz .LBB0_551
	s_nop 1
	v_mov_b64_e32 v[128:129], v[168:169]
	v_mov_b64_e32 v[130:131], v[170:171]
	v_mov_b64_e32 v[144:145], v[164:165]
	v_mov_b64_e32 v[146:147], v[166:167]
	v_mul_f32_e32 v142, 0xbfb8aa3b, v60
	v_exp_f32_e32 v142, v142
	v_mul_f32_e32 v143, 0xbfb8aa3b, v56
	v_exp_f32_e32 v143, v143
	v_add_f32_e32 v142, 1.0, v142
	v_rcp_f32_e32 v142, v142
	v_add_f32_e32 v143, 1.0, v143
	v_rcp_f32_e32 v143, v143
	v_sub_f32_e32 v139, 1.0, v144
	v_fma_f32 v139, v142, v139, v144
	v_sub_f32_e32 v142, 1.0, v128
	v_fma_f32 v128, v143, v142, v128
	v_mul_f32_e32 v143, 0xbfb8aa3b, v61
	v_exp_f32_e32 v143, v143
	v_sub_f32_e32 v142, 1.0, v145
	v_max_f32_e32 v139, 0x800000, v139
	v_max_f32_e32 v128, 0x800000, v128
	v_add_f32_e32 v143, 1.0, v143
	v_rcp_f32_e32 v143, v143
	v_log_f32_e32 v139, v139
	v_log_f32_e32 v128, v128
	v_fma_f32 v142, v143, v142, v145
	v_mul_f32_e32 v143, 0xbfb8aa3b, v57
	v_exp_f32_e32 v143, v143
	v_max_f32_e32 v142, 0x800000, v142
	v_log_f32_e32 v144, v142
	v_sub_f32_e32 v142, 1.0, v129
	v_add_f32_e32 v143, 1.0, v143
	v_rcp_f32_e32 v143, v143
	s_nop 0
	v_fma_f32 v129, v143, v142, v129
	v_mul_f32_e32 v143, 0xbfb8aa3b, v62
	v_exp_f32_e32 v143, v143
	v_sub_f32_e32 v142, 1.0, v146
	v_max_f32_e32 v129, 0x800000, v129
	v_log_f32_e32 v129, v129
	v_add_f32_e32 v143, 1.0, v143
	v_rcp_f32_e32 v143, v143
	s_nop 0
	v_fma_f32 v142, v143, v142, v146
	v_mul_f32_e32 v143, 0xbfb8aa3b, v58
	v_exp_f32_e32 v143, v143
	v_max_f32_e32 v142, 0x800000, v142
	v_log_f32_e32 v145, v142
	v_sub_f32_e32 v142, 1.0, v130
	v_add_f32_e32 v143, 1.0, v143
	v_rcp_f32_e32 v143, v143
	s_nop 0
	v_fma_f32 v130, v143, v142, v130
	v_mul_f32_e32 v143, 0xbfb8aa3b, v63
	v_exp_f32_e32 v143, v143
	v_sub_f32_e32 v142, 1.0, v147
	v_max_f32_e32 v130, 0x800000, v130
	v_log_f32_e32 v130, v130
	v_add_f32_e32 v143, 1.0, v143
	v_rcp_f32_e32 v143, v143
	s_nop 0
	v_fmac_f32_e32 v147, v143, v142
	v_mul_f32_e32 v143, 0xbfb8aa3b, v59
	v_exp_f32_e32 v143, v143
	v_max_f32_e32 v142, 0x800000, v147
	v_log_f32_e32 v146, v142
	v_sub_f32_e32 v142, 1.0, v131
	v_add_f32_e32 v143, 1.0, v143
	v_rcp_f32_e32 v143, v143
	s_nop 0
	v_fmac_f32_e32 v131, v143, v142
	v_max_f32_e32 v131, 0x800000, v131
	v_log_f32_e32 v131, v131

; __device__ __forceinline__ float sigm(float x) { return __builtin_amdgcn_rcpf(1.f + __builtin_amdgcn_exp2f(-1.44269504089f * x)); }
;     template <int KIND> __device__ __forceinline__ void seg(unsigned char* w, size_t dst, int ld, int cbase, const float* lb, const pg8::f32x4 (&acc)[2][2][4][2], const pg8::Unit& u, int wr, int wc, int fr, int fq) const {
;     ...
;                         const f32x4 l0 = *(const f32x4*)(lb + c), l1 = *(const f32x4*)(lb + c + 4);
;                         float r[8];
;                         if (lb0) {
; #pragma unroll
;                             for (int i = 0; i < 4; ++i) {
;                                 r[i] = fmaxf(-__log2f(1.f + __builtin_amdgcn_exp2f(-1.44269504089f * lo[i])), -126.f);
;                                 r[4 + i] = fmaxf(-__log2f(1.f + __builtin_amdgcn_exp2f(-1.44269504089f * hi[i])), -126.f);
;                             }
;                         } else {
; #pragma unroll
;                         for (int i = 0; i < 4; ++i) {
;                             const float f0 = l0[i] + (1.f - l0[i]) * sigm(lo[i]); r[i] = __log2f(fmaxf(f0, 1.17549435e-38f));
;                             const float f1 = l1[i] + (1.f - l1[i]) * sigm(hi[i]); r[4 + i] = __log2f(fmaxf(f1, 1.17549435e-38f));
;                         }
.LBB0_553:
	s_andn2_b64 vcc, exec, s[44:45]
	s_cbranch_vccnz .LBB0_555
	s_nop 1
	v_mov_b64_e32 v[128:129], v[176:177]
	v_mov_b64_e32 v[130:131], v[178:179]
	v_mov_b64_e32 v[144:145], v[172:173]
	v_mov_b64_e32 v[146:147], v[174:175]
	v_mul_f32_e32 v148, 0xbfb8aa3b, v52
	v_exp_f32_e32 v148, v148
	v_sub_f32_e32 v139, 1.0, v144
	v_add_f32_e32 v148, 1.0, v148
	v_rcp_f32_e32 v148, v148
	s_nop 0
	v_fma_f32 v139, v148, v139, v144
	v_mul_f32_e32 v148, 0xbfb8aa3b, v48
	v_exp_f32_e32 v148, v148
	v_sub_f32_e32 v144, 1.0, v128
	v_max_f32_e32 v139, 0x800000, v139
	v_log_f32_e32 v139, v139
	v_add_f32_e32 v148, 1.0, v148
	v_rcp_f32_e32 v148, v148
	s_nop 0
	v_fma_f32 v128, v148, v144, v128
	v_mul_f32_e32 v148, 0xbfb8aa3b, v53
	v_exp_f32_e32 v148, v148
	v_sub_f32_e32 v144, 1.0, v145
	v_max_f32_e32 v128, 0x800000, v128
	v_log_f32_e32 v128, v128
	v_add_f32_e32 v148, 1.0, v148
	v_rcp_f32_e32 v148, v148
	s_nop 0
	v_fma_f32 v144, v148, v144, v145
	v_mul_f32_e32 v148, 0xbfb8aa3b, v49
	v_exp_f32_e32 v148, v148
	v_sub_f32_e32 v145, 1.0, v129
	v_max_f32_e32 v144, 0x800000, v144
	v_log_f32_e32 v144, v144
	v_add_f32_e32 v148, 1.0, v148
	v_rcp_f32_e32 v148, v148
	s_nop 0
	v_fma_f32 v129, v148, v145, v129
	v_mul_f32_e32 v148, 0xbfb8aa3b, v54
	v_exp_f32_e32 v148, v148
	v_sub_f32_e32 v145, 1.0, v146
	v_max_f32_e32 v129, 0x800000, v129
	v_log_f32_e32 v129, v129
	v_add_f32_e32 v148, 1.0, v148
	v_rcp_f32_e32 v148, v148
	s_nop 0
	v_fma_f32 v145, v148, v145, v146
	v_mul_f32_e32 v148, 0xbfb8aa3b, v50
	v_exp_f32_e32 v148, v148
	v_sub_f32_e32 v146, 1.0, v130
	v_max_f32_e32 v145, 0x800000, v145
	v_log_f32_e32 v145, v145
	v_add_f32_e32 v148, 1.0, v148
	v_rcp_f32_e32 v148, v148
	s_nop 0
	v_fma_f32 v130, v148, v146, v130
	v_mul_f32_e32 v148, 0xbfb8aa3b, v55
	v_exp_f32_e32 v148, v148
	v_sub_f32_e32 v146, 1.0, v147
	v_max_f32_e32 v130, 0x800000, v130
	v_log_f32_e32 v130, v130
	v_add_f32_e32 v148, 1.0, v148
	v_rcp_f32_e32 v148, v148
	s_nop 0
	v_fmac_f32_e32 v147, v148, v146
	v_mul_f32_e32 v148, 0xbfb8aa3b, v51
	v_exp_f32_e32 v148, v148
	v_max_f32_e32 v146, 0x800000, v147
	v_sub_f32_e32 v147, 1.0, v131
	v_log_f32_e32 v146, v146
	v_add_f32_e32 v148, 1.0, v148
	v_rcp_f32_e32 v148, v148
	s_nop 0
	v_fmac_f32_e32 v131, v148, v147
	v_max_f32_e32 v131, 0x800000, v131
	v_log_f32_e32 v131, v131

; __device__ __forceinline__ float sigm(float x) { return __builtin_amdgcn_rcpf(1.f + __builtin_amdgcn_exp2f(-1.44269504089f * x)); }
;     template <int KIND> __device__ __forceinline__ void seg(unsigned char* w, size_t dst, int ld, int cbase, const float* lb, const pg8::f32x4 (&acc)[2][2][4][2], const pg8::Unit& u, int wr, int wc, int fr, int fq) const {
;     ...
;                         const f32x4 l0 = *(const f32x4*)(lb + c), l1 = *(const f32x4*)(lb + c + 4);
;                         float r[8];
;                         if (lb0) {
; #pragma unroll
;                             for (int i = 0; i < 4; ++i) {
;                                 r[i] = fmaxf(-__log2f(1.f + __builtin_amdgcn_exp2f(-1.44269504089f * lo[i])), -126.f);
;                                 r[4 + i] = fmaxf(-__log2f(1.f + __builtin_amdgcn_exp2f(-1.44269504089f * hi[i])), -126.f);
;                             }
;                         } else {
; #pragma unroll
;                         for (int i = 0; i < 4; ++i) {
;                             const float f0 = l0[i] + (1.f - l0[i]) * sigm(lo[i]); r[i] = __log2f(fmaxf(f0, 1.17549435e-38f));
;                             const float f1 = l1[i] + (1.f - l1[i]) * sigm(hi[i]); r[4 + i] = __log2f(fmaxf(f1, 1.17549435e-38f));
;                         }
.LBB0_557:
	s_andn2_b64 vcc, exec, s[44:45]
	s_cbranch_vccnz .LBB0_559
	s_nop 1
	v_mov_b64_e32 v[128:129], v[168:169]
	v_mov_b64_e32 v[130:131], v[170:171]
	v_mov_b64_e32 v[144:145], v[164:165]
	v_mov_b64_e32 v[146:147], v[166:167]
	v_mul_f32_e32 v142, 0xbfb8aa3b, v44
	v_exp_f32_e32 v142, v142
	v_mul_f32_e32 v143, 0xbfb8aa3b, v40
	v_exp_f32_e32 v143, v143
	v_add_f32_e32 v142, 1.0, v142
	v_rcp_f32_e32 v142, v142
	v_add_f32_e32 v143, 1.0, v143
	v_rcp_f32_e32 v143, v143
	v_sub_f32_e32 v139, 1.0, v144
	v_fma_f32 v139, v142, v139, v144
	v_sub_f32_e32 v142, 1.0, v128
	v_fma_f32 v128, v143, v142, v128
	v_mul_f32_e32 v143, 0xbfb8aa3b, v45
	v_exp_f32_e32 v143, v143
	v_sub_f32_e32 v142, 1.0, v145
	v_max_f32_e32 v139, 0x800000, v139
	v_max_f32_e32 v128, 0x800000, v128
	v_add_f32_e32 v143, 1.0, v143
	v_rcp_f32_e32 v143, v143
	v_log_f32_e32 v139, v139
	v_log_f32_e32 v128, v128
	v_fma_f32 v142, v143, v142, v145
	v_mul_f32_e32 v143, 0xbfb8aa3b, v41
	v_exp_f32_e32 v143, v143
	v_max_f32_e32 v142, 0x800000, v142
	v_log_f32_e32 v144, v142
	v_sub_f32_e32 v142, 1.0, v129
	v_add_f32_e32 v143, 1.0, v143
	v_rcp_f32_e32 v143, v143
	s_nop 0
	v_fma_f32 v129, v143, v142, v129
	v_mul_f32_e32 v143, 0xbfb8aa3b, v46
	v_exp_f32_e32 v143, v143
	v_sub_f32_e32 v142, 1.0, v146
	v_max_f32_e32 v129, 0x800000, v129
	v_log_f32_e32 v129, v129
	v_add_f32_e32 v143, 1.0, v143
	v_rcp_f32_e32 v143, v143
	s_nop 0
	v_fma_f32 v142, v143, v142, v146
	v_mul_f32_e32 v143, 0xbfb8aa3b, v42
	v_exp_f32_e32 v143, v143
	v_max_f32_e32 v142, 0x800000, v142
	v_log_f32_e32 v145, v142
	v_sub_f32_e32 v142, 1.0, v130
	v_add_f32_e32 v143, 1.0, v143
	v_rcp_f32_e32 v143, v143
	s_nop 0
	v_fma_f32 v130, v143, v142, v130
	v_mul_f32_e32 v143, 0xbfb8aa3b, v47
	v_exp_f32_e32 v143, v143
	v_sub_f32_e32 v142, 1.0, v147
	v_max_f32_e32 v130, 0x800000, v130
	v_log_f32_e32 v130, v130
	v_add_f32_e32 v143, 1.0, v143
	v_rcp_f32_e32 v143, v143
	s_nop 0
	v_fmac_f32_e32 v147, v143, v142
	v_mul_f32_e32 v143, 0xbfb8aa3b, v43
	v_exp_f32_e32 v143, v143
	v_max_f32_e32 v142, 0x800000, v147
	v_log_f32_e32 v146, v142
	v_sub_f32_e32 v142, 1.0, v131
	v_add_f32_e32 v143, 1.0, v143
	v_rcp_f32_e32 v143, v143
	s_nop 0
	v_fmac_f32_e32 v131, v143, v142
	v_max_f32_e32 v131, 0x800000, v131
	v_log_f32_e32 v131, v131

; __device__ __forceinline__ float sigm(float x) { return __builtin_amdgcn_rcpf(1.f + __builtin_amdgcn_exp2f(-1.44269504089f * x)); }
;     template <int KIND> __device__ __forceinline__ void seg(unsigned char* w, size_t dst, int ld, int cbase, const float* lb, const pg8::f32x4 (&acc)[2][2][4][2], const pg8::Unit& u, int wr, int wc, int fr, int fq) const {
;     ...
;                         const f32x4 l0 = *(const f32x4*)(lb + c), l1 = *(const f32x4*)(lb + c + 4);
;                         float r[8];
;                         if (lb0) {
; #pragma unroll
;                             for (int i = 0; i < 4; ++i) {
;                                 r[i] = fmaxf(-__log2f(1.f + __builtin_amdgcn_exp2f(-1.44269504089f * lo[i])), -126.f);
;                                 r[4 + i] = fmaxf(-__log2f(1.f + __builtin_amdgcn_exp2f(-1.44269504089f * hi[i])), -126.f);
;                             }
;                         } else {
; #pragma unroll
;                         for (int i = 0; i < 4; ++i) {
;                             const float f0 = l0[i] + (1.f - l0[i]) * sigm(lo[i]); r[i] = __log2f(fmaxf(f0, 1.17549435e-38f));
;                             const float f1 = l1[i] + (1.f - l1[i]) * sigm(hi[i]); r[4 + i] = __log2f(fmaxf(f1, 1.17549435e-38f));
;                         }
.LBB0_561:
	s_andn2_b64 vcc, exec, s[44:45]
	s_cbranch_vccnz .LBB0_563
	s_nop 1
	v_mov_b64_e32 v[128:129], v[176:177]
	v_mov_b64_e32 v[130:131], v[178:179]
	v_mov_b64_e32 v[144:145], v[172:173]
	v_mov_b64_e32 v[146:147], v[174:175]
	v_mul_f32_e32 v148, 0xbfb8aa3b, v36
	v_exp_f32_e32 v148, v148
	v_sub_f32_e32 v139, 1.0, v144
	v_add_f32_e32 v148, 1.0, v148
	v_rcp_f32_e32 v148, v148
	s_nop 0
	v_fma_f32 v139, v148, v139, v144
	v_mul_f32_e32 v148, 0xbfb8aa3b, v32
	v_exp_f32_e32 v148, v148
	v_sub_f32_e32 v144, 1.0, v128
	v_max_f32_e32 v139, 0x800000, v139
	v_log_f32_e32 v139, v139
	v_add_f32_e32 v148, 1.0, v148
	v_rcp_f32_e32 v148, v148
	s_nop 0
	v_fma_f32 v128, v148, v144, v128
	v_mul_f32_e32 v148, 0xbfb8aa3b, v37
	v_exp_f32_e32 v148, v148
	v_sub_f32_e32 v144, 1.0, v145
	v_max_f32_e32 v128, 0x800000, v128
	v_log_f32_e32 v128, v128
	v_add_f32_e32 v148, 1.0, v148
	v_rcp_f32_e32 v148, v148
	s_nop 0
	v_fma_f32 v144, v148, v144, v145
	v_mul_f32_e32 v148, 0xbfb8aa3b, v33
	v_exp_f32_e32 v148, v148
	v_sub_f32_e32 v145, 1.0, v129
	v_max_f32_e32 v144, 0x800000, v144
	v_log_f32_e32 v144, v144
	v_add_f32_e32 v148, 1.0, v148
	v_rcp_f32_e32 v148, v148
	s_nop 0
	v_fma_f32 v129, v148, v145, v129
	v_mul_f32_e32 v148, 0xbfb8aa3b, v38
	v_exp_f32_e32 v148, v148
	v_sub_f32_e32 v145, 1.0, v146
	v_max_f32_e32 v129, 0x800000, v129
	v_log_f32_e32 v129, v129
	v_add_f32_e32 v148, 1.0, v148
	v_rcp_f32_e32 v148, v148
	s_nop 0
	v_fma_f32 v145, v148, v145, v146
	v_mul_f32_e32 v148, 0xbfb8aa3b, v34
	v_exp_f32_e32 v148, v148
	v_sub_f32_e32 v146, 1.0, v130
	v_max_f32_e32 v145, 0x800000, v145
	v_log_f32_e32 v145, v145
	v_add_f32_e32 v148, 1.0, v148
	v_rcp_f32_e32 v148, v148
	s_nop 0
	v_fma_f32 v130, v148, v146, v130
	v_mul_f32_e32 v148, 0xbfb8aa3b, v39
	v_exp_f32_e32 v148, v148
	v_sub_f32_e32 v146, 1.0, v147
	v_max_f32_e32 v130, 0x800000, v130
	v_log_f32_e32 v130, v130
	v_add_f32_e32 v148, 1.0, v148
	v_rcp_f32_e32 v148, v148
	s_nop 0
	v_fmac_f32_e32 v147, v148, v146
	v_mul_f32_e32 v148, 0xbfb8aa3b, v35
	v_exp_f32_e32 v148, v148
	v_max_f32_e32 v146, 0x800000, v147
	v_sub_f32_e32 v147, 1.0, v131
	v_log_f32_e32 v146, v146
	v_add_f32_e32 v148, 1.0, v148
	v_rcp_f32_e32 v148, v148
	s_nop 0
	v_fmac_f32_e32 v131, v148, v147
	v_max_f32_e32 v131, 0x800000, v131
	v_log_f32_e32 v131, v131

; __device__ __forceinline__ float sigm(float x) { return __builtin_amdgcn_rcpf(1.f + __builtin_amdgcn_exp2f(-1.44269504089f * x)); }
;     template <int KIND> __device__ __forceinline__ void seg(unsigned char* w, size_t dst, int ld, int cbase, const float* lb, const pg8::f32x4 (&acc)[2][2][4][2], const pg8::Unit& u, int wr, int wc, int fr, int fq) const {
;     ...
;                         const f32x4 l0 = *(const f32x4*)(lb + c), l1 = *(const f32x4*)(lb + c + 4);
;                         float r[8];
;                         if (lb0) {
; #pragma unroll
;                             for (int i = 0; i < 4; ++i) {
;                                 r[i] = fmaxf(-__log2f(1.f + __builtin_amdgcn_exp2f(-1.44269504089f * lo[i])), -126.f);
;                                 r[4 + i] = fmaxf(-__log2f(1.f + __builtin_amdgcn_exp2f(-1.44269504089f * hi[i])), -126.f);
;                             }
;                         } else {
; #pragma unroll
;                         for (int i = 0; i < 4; ++i) {
;                             const float f0 = l0[i] + (1.f - l0[i]) * sigm(lo[i]); r[i] = __log2f(fmaxf(f0, 1.17549435e-38f));
;                             const float f1 = l1[i] + (1.f - l1[i]) * sigm(hi[i]); r[4 + i] = __log2f(fmaxf(f1, 1.17549435e-38f));
;                         }
.LBB0_565:
	s_andn2_b64 vcc, exec, s[44:45]
	s_cbranch_vccnz .LBB0_567
	s_nop 1
	v_mov_b64_e32 v[128:129], v[168:169]
	v_mov_b64_e32 v[130:131], v[170:171]
	v_mov_b64_e32 v[144:145], v[164:165]
	v_mov_b64_e32 v[146:147], v[166:167]
	v_mul_f32_e32 v142, 0xbfb8aa3b, v28
	v_exp_f32_e32 v142, v142
	v_mul_f32_e32 v143, 0xbfb8aa3b, v24
	v_exp_f32_e32 v143, v143
	v_add_f32_e32 v142, 1.0, v142
	v_rcp_f32_e32 v142, v142
	v_add_f32_e32 v143, 1.0, v143
	v_rcp_f32_e32 v143, v143
	v_sub_f32_e32 v139, 1.0, v144
	v_fma_f32 v139, v142, v139, v144
	v_sub_f32_e32 v142, 1.0, v128
	v_fma_f32 v128, v143, v142, v128
	v_mul_f32_e32 v143, 0xbfb8aa3b, v29
	v_exp_f32_e32 v143, v143
	v_sub_f32_e32 v142, 1.0, v145
	v_max_f32_e32 v139, 0x800000, v139
	v_max_f32_e32 v128, 0x800000, v128
	v_add_f32_e32 v143, 1.0, v143
	v_rcp_f32_e32 v143, v143
	v_log_f32_e32 v139, v139
	v_log_f32_e32 v128, v128
	v_fma_f32 v142, v143, v142, v145
	v_mul_f32_e32 v143, 0xbfb8aa3b, v25
	v_exp_f32_e32 v143, v143
	v_max_f32_e32 v142, 0x800000, v142
	v_log_f32_e32 v144, v142
	v_sub_f32_e32 v142, 1.0, v129
	v_add_f32_e32 v143, 1.0, v143
	v_rcp_f32_e32 v143, v143
	s_nop 0
	v_fma_f32 v129, v143, v142, v129
	v_mul_f32_e32 v143, 0xbfb8aa3b, v30
	v_exp_f32_e32 v143, v143
	v_sub_f32_e32 v142, 1.0, v146
	v_max_f32_e32 v129, 0x800000, v129
	v_log_f32_e32 v129, v129
	v_add_f32_e32 v143, 1.0, v143
	v_rcp_f32_e32 v143, v143
	s_nop 0
	v_fma_f32 v142, v143, v142, v146
	v_mul_f32_e32 v143, 0xbfb8aa3b, v26
	v_exp_f32_e32 v143, v143
	v_max_f32_e32 v142, 0x800000, v142
	v_log_f32_e32 v145, v142
	v_sub_f32_e32 v142, 1.0, v130
	v_add_f32_e32 v143, 1.0, v143
	v_rcp_f32_e32 v143, v143
	s_nop 0
	v_fma_f32 v130, v143, v142, v130
	v_mul_f32_e32 v143, 0xbfb8aa3b, v31
	v_exp_f32_e32 v143, v143
	v_sub_f32_e32 v142, 1.0, v147
	v_max_f32_e32 v130, 0x800000, v130
	v_log_f32_e32 v130, v130
	v_add_f32_e32 v143, 1.0, v143
	v_rcp_f32_e32 v143, v143
	s_nop 0
	v_fmac_f32_e32 v147, v143, v142
	v_mul_f32_e32 v143, 0xbfb8aa3b, v27
	v_exp_f32_e32 v143, v143
	v_max_f32_e32 v142, 0x800000, v147
	v_log_f32_e32 v146, v142
	v_sub_f32_e32 v142, 1.0, v131
	v_add_f32_e32 v143, 1.0, v143
	v_rcp_f32_e32 v143, v143
	s_nop 0
	v_fmac_f32_e32 v131, v143, v142
	v_max_f32_e32 v131, 0x800000, v131
	v_log_f32_e32 v131, v131

; __device__ __forceinline__ float sigm(float x) { return __builtin_amdgcn_rcpf(1.f + __builtin_amdgcn_exp2f(-1.44269504089f * x)); }
;     template <int KIND> __device__ __forceinline__ void seg(unsigned char* w, size_t dst, int ld, int cbase, const float* lb, const pg8::f32x4 (&acc)[2][2][4][2], const pg8::Unit& u, int wr, int wc, int fr, int fq) const {
;     ...
;                         const f32x4 l0 = *(const f32x4*)(lb + c), l1 = *(const f32x4*)(lb + c + 4);
;                         float r[8];
;                         if (lb0) {
; #pragma unroll
;                             for (int i = 0; i < 4; ++i) {
;                                 r[i] = fmaxf(-__log2f(1.f + __builtin_amdgcn_exp2f(-1.44269504089f * lo[i])), -126.f);
;                                 r[4 + i] = fmaxf(-__log2f(1.f + __builtin_amdgcn_exp2f(-1.44269504089f * hi[i])), -126.f);
;                             }
;                         } else {
; #pragma unroll
;                         for (int i = 0; i < 4; ++i) {
;                             const float f0 = l0[i] + (1.f - l0[i]) * sigm(lo[i]); r[i] = __log2f(fmaxf(f0, 1.17549435e-38f));
;                             const float f1 = l1[i] + (1.f - l1[i]) * sigm(hi[i]); r[4 + i] = __log2f(fmaxf(f1, 1.17549435e-38f));
;                         }
.LBB0_569:
	s_andn2_b64 vcc, exec, s[44:45]
	s_cbranch_vccnz .LBB0_571
	s_nop 1
	v_mov_b64_e32 v[128:129], v[176:177]
	v_mov_b64_e32 v[130:131], v[178:179]
	v_mov_b64_e32 v[144:145], v[172:173]
	v_mov_b64_e32 v[146:147], v[174:175]
	v_mul_f32_e32 v148, 0xbfb8aa3b, v20
	v_exp_f32_e32 v148, v148
	v_sub_f32_e32 v139, 1.0, v144
	v_add_f32_e32 v148, 1.0, v148
	v_rcp_f32_e32 v148, v148
	s_nop 0
	v_fma_f32 v139, v148, v139, v144
	v_mul_f32_e32 v148, 0xbfb8aa3b, v16
	v_exp_f32_e32 v148, v148
	v_sub_f32_e32 v144, 1.0, v128
	v_max_f32_e32 v139, 0x800000, v139
	v_log_f32_e32 v139, v139
	v_add_f32_e32 v148, 1.0, v148
	v_rcp_f32_e32 v148, v148
	s_nop 0
	v_fma_f32 v128, v148, v144, v128
	v_mul_f32_e32 v148, 0xbfb8aa3b, v21
	v_exp_f32_e32 v148, v148
	v_sub_f32_e32 v144, 1.0, v145
	v_max_f32_e32 v128, 0x800000, v128
	v_log_f32_e32 v128, v128
	v_add_f32_e32 v148, 1.0, v148
	v_rcp_f32_e32 v148, v148
	s_nop 0
	v_fma_f32 v144, v148, v144, v145
	v_mul_f32_e32 v148, 0xbfb8aa3b, v17
	v_exp_f32_e32 v148, v148
	v_sub_f32_e32 v145, 1.0, v129
	v_max_f32_e32 v144, 0x800000, v144
	v_log_f32_e32 v144, v144
	v_add_f32_e32 v148, 1.0, v148
	v_rcp_f32_e32 v148, v148
	s_nop 0
	v_fma_f32 v129, v148, v145, v129
	v_mul_f32_e32 v148, 0xbfb8aa3b, v22
	v_exp_f32_e32 v148, v148
	v_sub_f32_e32 v145, 1.0, v146
	v_max_f32_e32 v129, 0x800000, v129
	v_log_f32_e32 v129, v129
	v_add_f32_e32 v148, 1.0, v148
	v_rcp_f32_e32 v148, v148
	s_nop 0
	v_fma_f32 v145, v148, v145, v146
	v_mul_f32_e32 v148, 0xbfb8aa3b, v18
	v_exp_f32_e32 v148, v148
	v_sub_f32_e32 v146, 1.0, v130
	v_max_f32_e32 v145, 0x800000, v145
	v_log_f32_e32 v145, v145
	v_add_f32_e32 v148, 1.0, v148
	v_rcp_f32_e32 v148, v148
	s_nop 0
	v_fma_f32 v130, v148, v146, v130
	v_mul_f32_e32 v148, 0xbfb8aa3b, v23
	v_exp_f32_e32 v148, v148
	v_sub_f32_e32 v146, 1.0, v147
	v_max_f32_e32 v130, 0x800000, v130
	v_log_f32_e32 v130, v130
	v_add_f32_e32 v148, 1.0, v148
	v_rcp_f32_e32 v148, v148
	s_nop 0
	v_fmac_f32_e32 v147, v148, v146
	v_mul_f32_e32 v148, 0xbfb8aa3b, v19
	v_exp_f32_e32 v148, v148
	v_max_f32_e32 v146, 0x800000, v147
	v_sub_f32_e32 v147, 1.0, v131
	v_log_f32_e32 v146, v146
	v_add_f32_e32 v148, 1.0, v148
	v_rcp_f32_e32 v148, v148
	s_nop 0
	v_fmac_f32_e32 v131, v148, v147
	v_max_f32_e32 v131, 0x800000, v131
	v_log_f32_e32 v131, v131

; __device__ __forceinline__ float sigm(float x) { return __builtin_amdgcn_rcpf(1.f + __builtin_amdgcn_exp2f(-1.44269504089f * x)); }
;     template <int KIND> __device__ __forceinline__ void seg(unsigned char* w, size_t dst, int ld, int cbase, const float* lb, const pg8::f32x4 (&acc)[2][2][4][2], const pg8::Unit& u, int wr, int wc, int fr, int fq) const {
;     ...
;                         const f32x4 l0 = *(const f32x4*)(lb + c), l1 = *(const f32x4*)(lb + c + 4);
;                         float r[8];
;                         if (lb0) {
; #pragma unroll
;                             for (int i = 0; i < 4; ++i) {
;                                 r[i] = fmaxf(-__log2f(1.f + __builtin_amdgcn_exp2f(-1.44269504089f * lo[i])), -126.f);
;                                 r[4 + i] = fmaxf(-__log2f(1.f + __builtin_amdgcn_exp2f(-1.44269504089f * hi[i])), -126.f);
;                             }
;                         } else {
; #pragma unroll
;                         for (int i = 0; i < 4; ++i) {
;                             const float f0 = l0[i] + (1.f - l0[i]) * sigm(lo[i]); r[i] = __log2f(fmaxf(f0, 1.17549435e-38f));
;                             const float f1 = l1[i] + (1.f - l1[i]) * sigm(hi[i]); r[4 + i] = __log2f(fmaxf(f1, 1.17549435e-38f));
;                         }
.LBB0_573:
	s_andn2_b64 vcc, exec, s[44:45]
	s_cbranch_vccnz .LBB0_575
	s_nop 1
	v_mov_b64_e32 v[128:129], v[168:169]
	v_mov_b64_e32 v[130:131], v[170:171]
	v_mov_b64_e32 v[142:143], v[164:165]
	v_mov_b64_e32 v[144:145], v[166:167]
	v_mul_f32_e32 v135, 0xbfb8aa3b, v12
	v_exp_f32_e32 v135, v135
	v_sub_f32_e32 v134, 1.0, v142
	v_add_f32_e32 v135, 1.0, v135
	v_rcp_f32_e32 v135, v135
	s_nop 0
	v_fma_f32 v134, v135, v134, v142
	v_mul_f32_e32 v135, 0xbfb8aa3b, v8
	v_exp_f32_e32 v135, v135
	v_max_f32_e32 v134, 0x800000, v134
	v_log_f32_e32 v139, v134
	v_sub_f32_e32 v134, 1.0, v128
	v_add_f32_e32 v135, 1.0, v135
	v_rcp_f32_e32 v135, v135
	s_nop 0
	v_fma_f32 v128, v135, v134, v128
	v_mul_f32_e32 v135, 0xbfb8aa3b, v13
	v_exp_f32_e32 v135, v135
	v_sub_f32_e32 v134, 1.0, v143
	v_max_f32_e32 v128, 0x800000, v128
	v_log_f32_e32 v128, v128
	v_add_f32_e32 v135, 1.0, v135
	v_rcp_f32_e32 v135, v135
	s_nop 0
	v_fma_f32 v134, v135, v134, v143
	v_mul_f32_e32 v135, 0xbfb8aa3b, v9
	v_exp_f32_e32 v135, v135
	v_max_f32_e32 v134, 0x800000, v134
	v_log_f32_e32 v142, v134
	v_sub_f32_e32 v134, 1.0, v129
	v_add_f32_e32 v135, 1.0, v135
	v_rcp_f32_e32 v135, v135
	s_nop 0
	v_fma_f32 v129, v135, v134, v129
	v_mul_f32_e32 v135, 0xbfb8aa3b, v14
	v_exp_f32_e32 v135, v135
	v_sub_f32_e32 v134, 1.0, v144
	v_max_f32_e32 v129, 0x800000, v129
	v_log_f32_e32 v129, v129
	v_add_f32_e32 v135, 1.0, v135
	v_rcp_f32_e32 v135, v135
	s_nop 0
	v_fma_f32 v134, v135, v134, v144
	v_mul_f32_e32 v135, 0xbfb8aa3b, v10
	v_exp_f32_e32 v135, v135
	v_max_f32_e32 v134, 0x800000, v134
	v_log_f32_e32 v143, v134
	v_sub_f32_e32 v134, 1.0, v130
	v_add_f32_e32 v135, 1.0, v135
	v_rcp_f32_e32 v135, v135
	s_nop 0
	v_fma_f32 v130, v135, v134, v130
	v_mul_f32_e32 v135, 0xbfb8aa3b, v15
	v_exp_f32_e32 v135, v135
	v_sub_f32_e32 v134, 1.0, v145
	v_max_f32_e32 v130, 0x800000, v130
	v_log_f32_e32 v130, v130
	v_add_f32_e32 v135, 1.0, v135
	v_rcp_f32_e32 v135, v135
	s_nop 0
	v_fmac_f32_e32 v145, v135, v134
	v_mul_f32_e32 v135, 0xbfb8aa3b, v11
	v_exp_f32_e32 v135, v135
	v_max_f32_e32 v134, 0x800000, v145
	v_log_f32_e32 v144, v134
	v_sub_f32_e32 v134, 1.0, v131
	v_add_f32_e32 v135, 1.0, v135
	v_rcp_f32_e32 v135, v135
	s_nop 0
	v_fmac_f32_e32 v131, v135, v134
	v_max_f32_e32 v131, 0x800000, v131
	v_log_f32_e32 v131, v131

; __device__ __forceinline__ float sigm(float x) { return __builtin_amdgcn_rcpf(1.f + __builtin_amdgcn_exp2f(-1.44269504089f * x)); }
;     template <int KIND> __device__ __forceinline__ void seg(unsigned char* w, size_t dst, int ld, int cbase, const float* lb, const pg8::f32x4 (&acc)[2][2][4][2], const pg8::Unit& u, int wr, int wc, int fr, int fq) const {
;     ...
;                         const f32x4 l0 = *(const f32x4*)(lb + c), l1 = *(const f32x4*)(lb + c + 4);
;                         float r[8];
;                         if (lb0) {
; #pragma unroll
;                             for (int i = 0; i < 4; ++i) {
;                                 r[i] = fmaxf(-__log2f(1.f + __builtin_amdgcn_exp2f(-1.44269504089f * lo[i])), -126.f);
;                                 r[4 + i] = fmaxf(-__log2f(1.f + __builtin_amdgcn_exp2f(-1.44269504089f * hi[i])), -126.f);
;                             }
;                         } else {
; #pragma unroll
;                         for (int i = 0; i < 4; ++i) {
;                             const float f0 = l0[i] + (1.f - l0[i]) * sigm(lo[i]); r[i] = __log2f(fmaxf(f0, 1.17549435e-38f));
;                             const float f1 = l1[i] + (1.f - l1[i]) * sigm(hi[i]); r[4 + i] = __log2f(fmaxf(f1, 1.17549435e-38f));
;                         }
.LBB0_577:
	s_andn2_b64 vcc, exec, s[8:9]
	s_cbranch_vccnz .LBB0_579
	s_nop 1
	v_mov_b64_e32 v[128:129], v[176:177]
	v_mov_b64_e32 v[130:131], v[178:179]
	v_mov_b64_e32 v[136:137], v[172:173]
	v_mov_b64_e32 v[138:139], v[174:175]
	v_mul_f32_e32 v133, 0xbfb8aa3b, v4
	v_exp_f32_e32 v133, v133
	v_sub_f32_e32 v132, 1.0, v136
	v_add_f32_e32 v133, 1.0, v133
	v_rcp_f32_e32 v133, v133
	s_nop 0
	v_fma_f32 v132, v133, v132, v136
	v_mul_f32_e32 v136, 0xbfb8aa3b, v0
	v_exp_f32_e32 v136, v136
	v_sub_f32_e32 v133, 1.0, v128
	v_max_f32_e32 v132, 0x800000, v132
	v_log_f32_e32 v132, v132
	v_add_f32_e32 v136, 1.0, v136
	v_rcp_f32_e32 v136, v136
	s_nop 0
	v_fma_f32 v128, v136, v133, v128
	v_mul_f32_e32 v136, 0xbfb8aa3b, v5
	v_exp_f32_e32 v136, v136
	v_sub_f32_e32 v133, 1.0, v137
	v_max_f32_e32 v128, 0x800000, v128
	v_log_f32_e32 v128, v128
	v_add_f32_e32 v136, 1.0, v136
	v_rcp_f32_e32 v136, v136
	s_nop 0
	v_fma_f32 v133, v136, v133, v137
	v_mul_f32_e32 v137, 0xbfb8aa3b, v1
	v_exp_f32_e32 v137, v137
	v_sub_f32_e32 v136, 1.0, v129
	v_max_f32_e32 v133, 0x800000, v133
	v_log_f32_e32 v133, v133
	v_add_f32_e32 v137, 1.0, v137
	v_rcp_f32_e32 v137, v137
	s_nop 0
	v_fma_f32 v129, v137, v136, v129
	v_mul_f32_e32 v137, 0xbfb8aa3b, v6
	v_exp_f32_e32 v137, v137
	v_sub_f32_e32 v136, 1.0, v138
	v_max_f32_e32 v129, 0x800000, v129
	v_log_f32_e32 v129, v129
	v_add_f32_e32 v137, 1.0, v137
	v_rcp_f32_e32 v137, v137
	s_nop 0
	v_fma_f32 v136, v137, v136, v138
	v_mul_f32_e32 v137, 0xbfb8aa3b, v2
	v_exp_f32_e32 v137, v137
	v_max_f32_e32 v136, 0x800000, v136
	v_log_f32_e32 v138, v136
	v_sub_f32_e32 v136, 1.0, v130
	v_add_f32_e32 v137, 1.0, v137
	v_rcp_f32_e32 v137, v137
	s_nop 0
	v_fma_f32 v130, v137, v136, v130
	v_mul_f32_e32 v137, 0xbfb8aa3b, v7
	v_exp_f32_e32 v137, v137
	v_sub_f32_e32 v136, 1.0, v139
	v_max_f32_e32 v130, 0x800000, v130
	v_log_f32_e32 v130, v130
	v_add_f32_e32 v137, 1.0, v137
	v_rcp_f32_e32 v137, v137
	s_nop 0
	v_fmac_f32_e32 v139, v137, v136
	v_mul_f32_e32 v137, 0xbfb8aa3b, v3
	v_exp_f32_e32 v137, v137
	v_max_f32_e32 v136, 0x800000, v139
	v_log_f32_e32 v139, v136
	v_sub_f32_e32 v136, 1.0, v131
	v_add_f32_e32 v137, 1.0, v137
	v_rcp_f32_e32 v137, v137
	s_nop 0
	v_fmac_f32_e32 v131, v137, v136
	v_max_f32_e32 v131, 0x800000, v131
	v_log_f32_e32 v131, v131

; __device__ __forceinline__ float sigm(float x) { return __builtin_amdgcn_rcpf(1.f + __builtin_amdgcn_exp2f(-1.44269504089f * x)); }
; __device__ __forceinline__ unsigned f2h(float x) { _Float16 h = (_Float16)x; return (unsigned)__builtin_bit_cast(unsigned short, h); }
;     template <int KIND> __device__ __forceinline__ void seg(unsigned char* w, size_t dst, int ld, int cbase, const float* lb, const pg8::f32x4 (&acc)[2][2][4][2], const pg8::Unit& u, int wr, int wc, int fr, int fq) const {
;     ...
;                     const int c = u.pn * 256 + bj * 128 + wc * 32 + 8 * fq - cbase;
;                     f32x4 lo = acc[ai][bj][m][0], hi = acc[ai][bj][m][1];
;                     if (KIND == 4) {
;                         const f32x4 l0 = *(const f32x4*)(lb + c), l1 = *(const f32x4*)(lb + c + 4);
;                         float r[8];
;                         if (lb0) {
; #pragma unroll
;                             for (int i = 0; i < 4; ++i) {
;                                 r[i] = fmaxf(-__log2f(1.f + __builtin_amdgcn_exp2f(-1.44269504089f * lo[i])), -126.f);
;                                 r[4 + i] = fmaxf(-__log2f(1.f + __builtin_amdgcn_exp2f(-1.44269504089f * hi[i])), -126.f);
;                             }
;                         } else {
; #pragma unroll
;                         for (int i = 0; i < 4; ++i) {
;                             const float f0 = l0[i] + (1.f - l0[i]) * sigm(lo[i]); r[i] = __log2f(fmaxf(f0, 1.17549435e-38f));
;                             const float f1 = l1[i] + (1.f - l1[i]) * sigm(hi[i]); r[4 + i] = __log2f(fmaxf(f1, 1.17549435e-38f));
;                         }
;                         }
;                         u32x4 v; v.x = f2h(r[0]) | (f2h(r[1]) << 16); v.y = f2h(r[2]) | (f2h(r[3]) << 16); v.z = f2h(r[4]) | (f2h(r[5]) << 16); v.w = f2h(r[6]) | (f2h(r[7]) << 16);
;                         *(u32x4*)((unsigned short*)(w + dst) + (size_t)row * ld + c) = v;
.LBB0_584:
	s_lshl_b32 s0, s15, 5
	v_lshl_or_b32 v134, v187, 3, s0
	v_or_b32_e32 v134, 0xfffffc00, v134
	s_lshl_b32 s0, s22, 8
	v_add_u32_e32 v192, s0, v134
	s_andn2_b64 vcc, exec, s[44:45]
	v_lshl_add_u64 v[134:135], v[192:193], 2, s[78:79]
	s_cbranch_vccnz .LBB0_586
	flat_load_dwordx4 v[168:171], v[134:135] offset:16
	flat_load_dwordx4 v[164:167], v[134:135]
	flat_load_dwordx4 v[176:179], v[134:135] offset:528
	flat_load_dwordx4 v[172:175], v[134:135] offset:512
	v_mul_f32_e32 v133, 0xbfb8aa3b, v124
	v_exp_f32_e32 v133, v133
	s_waitcnt vmcnt(0) lgkmcnt(0)
	v_mov_b64_e32 v[128:129], v[168:169]
	v_mov_b64_e32 v[130:131], v[170:171]
	v_mov_b64_e32 v[136:137], v[164:165]
	v_mov_b64_e32 v[138:139], v[166:167]
	v_sub_f32_e32 v132, 1.0, v136
	v_add_f32_e32 v133, 1.0, v133
	v_rcp_f32_e32 v133, v133
	s_nop 0
	v_fma_f32 v132, v133, v132, v136
	v_mul_f32_e32 v136, 0xbfb8aa3b, v120
	v_exp_f32_e32 v136, v136
	v_sub_f32_e32 v133, 1.0, v128
	v_max_f32_e32 v132, 0x800000, v132
	v_log_f32_e32 v132, v132
	v_add_f32_e32 v136, 1.0, v136
	v_rcp_f32_e32 v136, v136
	s_nop 0
	v_fma_f32 v128, v136, v133, v128
	v_mul_f32_e32 v136, 0xbfb8aa3b, v125
	v_exp_f32_e32 v136, v136
	v_sub_f32_e32 v133, 1.0, v137
	v_max_f32_e32 v128, 0x800000, v128
	v_log_f32_e32 v128, v128
	v_add_f32_e32 v136, 1.0, v136
	v_rcp_f32_e32 v136, v136
	s_nop 0
	v_fma_f32 v133, v136, v133, v137
	v_mul_f32_e32 v137, 0xbfb8aa3b, v121
	v_exp_f32_e32 v137, v137
	v_sub_f32_e32 v136, 1.0, v129
	v_max_f32_e32 v133, 0x800000, v133
	v_log_f32_e32 v133, v133
	v_add_f32_e32 v137, 1.0, v137
	v_rcp_f32_e32 v137, v137
	s_nop 0
	v_fma_f32 v129, v137, v136, v129
	v_mul_f32_e32 v137, 0xbfb8aa3b, v126
	v_exp_f32_e32 v137, v137
	v_sub_f32_e32 v136, 1.0, v138
	v_max_f32_e32 v129, 0x800000, v129
	v_log_f32_e32 v129, v129
	v_add_f32_e32 v137, 1.0, v137
	v_rcp_f32_e32 v137, v137
	s_nop 0
	v_fma_f32 v136, v137, v136, v138
	v_mul_f32_e32 v138, 0xbfb8aa3b, v122
	v_exp_f32_e32 v138, v138
	v_sub_f32_e32 v137, 1.0, v130
	v_max_f32_e32 v136, 0x800000, v136
	v_log_f32_e32 v136, v136
	v_add_f32_e32 v138, 1.0, v138
	v_rcp_f32_e32 v138, v138
	s_nop 0
	v_fma_f32 v130, v138, v137, v130
	v_mul_f32_e32 v138, 0xbfb8aa3b, v127
	v_exp_f32_e32 v138, v138
	v_sub_f32_e32 v137, 1.0, v139
	v_max_f32_e32 v130, 0x800000, v130
	v_log_f32_e32 v130, v130
	v_add_f32_e32 v138, 1.0, v138
	v_rcp_f32_e32 v138, v138
	s_nop 0
	v_fmac_f32_e32 v139, v138, v137
	v_max_f32_e32 v137, 0x800000, v139
	v_mul_f32_e32 v139, 0xbfb8aa3b, v123
	v_exp_f32_e32 v139, v139
	v_sub_f32_e32 v138, 1.0, v131
	v_log_f32_e32 v137, v137
	v_add_f32_e32 v139, 1.0, v139
	v_rcp_f32_e32 v139, v139
	s_nop 0
	v_fmac_f32_e32 v131, v139, v138
	v_max_f32_e32 v131, 0x800000, v131
	v_log_f32_e32 v131, v131

; __device__ __forceinline__ float sigm(float x) { return __builtin_amdgcn_rcpf(1.f + __builtin_amdgcn_exp2f(-1.44269504089f * x)); }
;     template <int KIND> __device__ __forceinline__ void seg(unsigned char* w, size_t dst, int ld, int cbase, const float* lb, const pg8::f32x4 (&acc)[2][2][4][2], const pg8::Unit& u, int wr, int wc, int fr, int fq) const {
;     ...
;                         const f32x4 l0 = *(const f32x4*)(lb + c), l1 = *(const f32x4*)(lb + c + 4);
;                         float r[8];
;                         if (lb0) {
; #pragma unroll
;                             for (int i = 0; i < 4; ++i) {
;                                 r[i] = fmaxf(-__log2f(1.f + __builtin_amdgcn_exp2f(-1.44269504089f * lo[i])), -126.f);
;                                 r[4 + i] = fmaxf(-__log2f(1.f + __builtin_amdgcn_exp2f(-1.44269504089f * hi[i])), -126.f);
;                             }
;                         } else {
; #pragma unroll
;                         for (int i = 0; i < 4; ++i) {
;                             const float f0 = l0[i] + (1.f - l0[i]) * sigm(lo[i]); r[i] = __log2f(fmaxf(f0, 1.17549435e-38f));
;                             const float f1 = l1[i] + (1.f - l1[i]) * sigm(hi[i]); r[4 + i] = __log2f(fmaxf(f1, 1.17549435e-38f));
;                         }
.LBB0_588:
	v_add_u32_e32 v132, 0x80, v192
	v_mov_b32_e32 v133, v193
	s_andn2_b64 vcc, exec, s[44:45]
	v_lshl_add_u64 v[136:137], v[132:133], 2, s[78:79]
	s_cbranch_vccnz .LBB0_590
	s_nop 1
	v_mov_b64_e32 v[128:129], v[176:177]
	v_mov_b64_e32 v[130:131], v[178:179]
	v_mov_b64_e32 v[144:145], v[172:173]
	v_mov_b64_e32 v[146:147], v[174:175]
	v_mul_f32_e32 v143, 0xbfb8aa3b, v116
	v_exp_f32_e32 v143, v143
	v_sub_f32_e32 v139, 1.0, v144
	v_add_f32_e32 v143, 1.0, v143
	v_rcp_f32_e32 v143, v143
	s_nop 0
	v_fma_f32 v139, v143, v139, v144
	v_mul_f32_e32 v144, 0xbfb8aa3b, v112
	v_exp_f32_e32 v144, v144
	v_sub_f32_e32 v143, 1.0, v128
	v_max_f32_e32 v139, 0x800000, v139
	v_log_f32_e32 v139, v139
	v_add_f32_e32 v144, 1.0, v144
	v_rcp_f32_e32 v144, v144
	s_nop 0
	v_fma_f32 v128, v144, v143, v128
	v_mul_f32_e32 v144, 0xbfb8aa3b, v117
	v_exp_f32_e32 v144, v144
	v_sub_f32_e32 v143, 1.0, v145
	v_max_f32_e32 v128, 0x800000, v128
	v_log_f32_e32 v128, v128
	v_add_f32_e32 v144, 1.0, v144
	v_rcp_f32_e32 v144, v144
	s_nop 0
	v_fma_f32 v143, v144, v143, v145
	v_mul_f32_e32 v145, 0xbfb8aa3b, v113
	v_exp_f32_e32 v145, v145
	v_sub_f32_e32 v144, 1.0, v129
	v_max_f32_e32 v143, 0x800000, v143
	v_log_f32_e32 v143, v143
	v_add_f32_e32 v145, 1.0, v145
	v_rcp_f32_e32 v145, v145
	s_nop 0
	v_fma_f32 v129, v145, v144, v129
	v_mul_f32_e32 v145, 0xbfb8aa3b, v118
	v_exp_f32_e32 v145, v145
	v_sub_f32_e32 v144, 1.0, v146
	v_max_f32_e32 v129, 0x800000, v129
	v_log_f32_e32 v129, v129
	v_add_f32_e32 v145, 1.0, v145
	v_rcp_f32_e32 v145, v145
	s_nop 0
	v_fma_f32 v144, v145, v144, v146
	v_mul_f32_e32 v146, 0xbfb8aa3b, v114
	v_exp_f32_e32 v146, v146
	v_sub_f32_e32 v145, 1.0, v130
	v_max_f32_e32 v144, 0x800000, v144
	v_log_f32_e32 v144, v144
	v_add_f32_e32 v146, 1.0, v146
	v_rcp_f32_e32 v146, v146
	s_nop 0
	v_fma_f32 v130, v146, v145, v130
	v_mul_f32_e32 v146, 0xbfb8aa3b, v119
	v_exp_f32_e32 v146, v146
	v_sub_f32_e32 v145, 1.0, v147
	v_max_f32_e32 v130, 0x800000, v130
	v_log_f32_e32 v130, v130
	v_add_f32_e32 v146, 1.0, v146
	v_rcp_f32_e32 v146, v146
	s_nop 0
	v_fmac_f32_e32 v147, v146, v145
	v_max_f32_e32 v145, 0x800000, v147
	v_mul_f32_e32 v147, 0xbfb8aa3b, v115
	v_exp_f32_e32 v147, v147
	v_sub_f32_e32 v146, 1.0, v131
	v_log_f32_e32 v145, v145
	v_add_f32_e32 v147, 1.0, v147
	v_rcp_f32_e32 v147, v147
	s_nop 0
	v_fmac_f32_e32 v131, v147, v146
	v_max_f32_e32 v131, 0x800000, v131
	v_log_f32_e32 v131, v131

; __device__ __forceinline__ float sigm(float x) { return __builtin_amdgcn_rcpf(1.f + __builtin_amdgcn_exp2f(-1.44269504089f * x)); }
;     template <int KIND> __device__ __forceinline__ void seg(unsigned char* w, size_t dst, int ld, int cbase, const float* lb, const pg8::f32x4 (&acc)[2][2][4][2], const pg8::Unit& u, int wr, int wc, int fr, int fq) const {
;     ...
;                         const f32x4 l0 = *(const f32x4*)(lb + c), l1 = *(const f32x4*)(lb + c + 4);
;                         float r[8];
;                         if (lb0) {
; #pragma unroll
;                             for (int i = 0; i < 4; ++i) {
;                                 r[i] = fmaxf(-__log2f(1.f + __builtin_amdgcn_exp2f(-1.44269504089f * lo[i])), -126.f);
;                                 r[4 + i] = fmaxf(-__log2f(1.f + __builtin_amdgcn_exp2f(-1.44269504089f * hi[i])), -126.f);
;                             }
;                         } else {
; #pragma unroll
;                         for (int i = 0; i < 4; ++i) {
;                             const float f0 = l0[i] + (1.f - l0[i]) * sigm(lo[i]); r[i] = __log2f(fmaxf(f0, 1.17549435e-38f));
;                             const float f1 = l1[i] + (1.f - l1[i]) * sigm(hi[i]); r[4 + i] = __log2f(fmaxf(f1, 1.17549435e-38f));
;                         }
.LBB0_592:
	s_andn2_b64 vcc, exec, s[44:45]
	s_cbranch_vccnz .LBB0_594
	s_nop 1
	v_mov_b64_e32 v[128:129], v[168:169]
	v_mov_b64_e32 v[130:131], v[170:171]
	v_mov_b64_e32 v[144:145], v[164:165]
	v_mov_b64_e32 v[146:147], v[166:167]
	v_mul_f32_e32 v140, 0xbfb8aa3b, v108
	v_exp_f32_e32 v140, v140
	v_mul_f32_e32 v141, 0xbfb8aa3b, v104
	v_exp_f32_e32 v141, v141
	v_add_f32_e32 v140, 1.0, v140
	v_rcp_f32_e32 v140, v140
	v_add_f32_e32 v141, 1.0, v141
	v_rcp_f32_e32 v141, v141
	v_sub_f32_e32 v139, 1.0, v144
	v_fma_f32 v139, v140, v139, v144
	v_sub_f32_e32 v140, 1.0, v128
	v_fma_f32 v128, v141, v140, v128
	v_mul_f32_e32 v141, 0xbfb8aa3b, v109
	v_exp_f32_e32 v141, v141
	v_sub_f32_e32 v140, 1.0, v145
	v_max_f32_e32 v139, 0x800000, v139
	v_max_f32_e32 v128, 0x800000, v128
	v_add_f32_e32 v141, 1.0, v141
	v_rcp_f32_e32 v141, v141
	v_log_f32_e32 v139, v139
	v_log_f32_e32 v128, v128
	v_fma_f32 v140, v141, v140, v145
	v_mul_f32_e32 v141, 0xbfb8aa3b, v105
	v_exp_f32_e32 v141, v141
	v_max_f32_e32 v140, 0x800000, v140
	v_log_f32_e32 v143, v140
	v_sub_f32_e32 v140, 1.0, v129
	v_add_f32_e32 v141, 1.0, v141
	v_rcp_f32_e32 v141, v141
	s_nop 0
	v_fma_f32 v129, v141, v140, v129
	v_mul_f32_e32 v141, 0xbfb8aa3b, v110
	v_exp_f32_e32 v141, v141
	v_sub_f32_e32 v140, 1.0, v146
	v_max_f32_e32 v129, 0x800000, v129
	v_log_f32_e32 v129, v129
	v_add_f32_e32 v141, 1.0, v141
	v_rcp_f32_e32 v141, v141
	s_nop 0
	v_fma_f32 v140, v141, v140, v146
	v_mul_f32_e32 v141, 0xbfb8aa3b, v106
	v_exp_f32_e32 v141, v141
	v_max_f32_e32 v140, 0x800000, v140
	v_log_f32_e32 v144, v140
	v_sub_f32_e32 v140, 1.0, v130
	v_add_f32_e32 v141, 1.0, v141
	v_rcp_f32_e32 v141, v141
	s_nop 0
	v_fma_f32 v130, v141, v140, v130
	v_mul_f32_e32 v141, 0xbfb8aa3b, v111
	v_exp_f32_e32 v141, v141
	v_sub_f32_e32 v140, 1.0, v147
	v_max_f32_e32 v130, 0x800000, v130
	v_log_f32_e32 v130, v130
	v_add_f32_e32 v141, 1.0, v141
	v_rcp_f32_e32 v141, v141
	s_nop 0
	v_fmac_f32_e32 v147, v141, v140
	v_mul_f32_e32 v141, 0xbfb8aa3b, v107
	v_exp_f32_e32 v141, v141
	v_max_f32_e32 v140, 0x800000, v147
	v_log_f32_e32 v145, v140
	v_sub_f32_e32 v140, 1.0, v131
	v_add_f32_e32 v141, 1.0, v141
	v_rcp_f32_e32 v141, v141
	s_nop 0
	v_fmac_f32_e32 v131, v141, v140
	v_max_f32_e32 v131, 0x800000, v131
	v_log_f32_e32 v131, v131

; __device__ __forceinline__ float sigm(float x) { return __builtin_amdgcn_rcpf(1.f + __builtin_amdgcn_exp2f(-1.44269504089f * x)); }
;     template <int KIND> __device__ __forceinline__ void seg(unsigned char* w, size_t dst, int ld, int cbase, const float* lb, const pg8::f32x4 (&acc)[2][2][4][2], const pg8::Unit& u, int wr, int wc, int fr, int fq) const {
;     ...
;                         const f32x4 l0 = *(const f32x4*)(lb + c), l1 = *(const f32x4*)(lb + c + 4);
;                         float r[8];
;                         if (lb0) {
; #pragma unroll
;                             for (int i = 0; i < 4; ++i) {
;                                 r[i] = fmaxf(-__log2f(1.f + __builtin_amdgcn_exp2f(-1.44269504089f * lo[i])), -126.f);
;                                 r[4 + i] = fmaxf(-__log2f(1.f + __builtin_amdgcn_exp2f(-1.44269504089f * hi[i])), -126.f);
;                             }
;                         } else {
; #pragma unroll
;                         for (int i = 0; i < 4; ++i) {
;                             const float f0 = l0[i] + (1.f - l0[i]) * sigm(lo[i]); r[i] = __log2f(fmaxf(f0, 1.17549435e-38f));
;                             const float f1 = l1[i] + (1.f - l1[i]) * sigm(hi[i]); r[4 + i] = __log2f(fmaxf(f1, 1.17549435e-38f));
;                         }
.LBB0_596:
	s_andn2_b64 vcc, exec, s[44:45]
	s_cbranch_vccnz .LBB0_598
	s_nop 1
	v_mov_b64_e32 v[128:129], v[176:177]
	v_mov_b64_e32 v[130:131], v[178:179]
	v_mov_b64_e32 v[144:145], v[172:173]
	v_mov_b64_e32 v[146:147], v[174:175]
	v_mul_f32_e32 v143, 0xbfb8aa3b, v100
	v_exp_f32_e32 v143, v143
	v_sub_f32_e32 v139, 1.0, v144
	v_add_f32_e32 v143, 1.0, v143
	v_rcp_f32_e32 v143, v143
	s_nop 0
	v_fma_f32 v139, v143, v139, v144
	v_mul_f32_e32 v144, 0xbfb8aa3b, v96
	v_exp_f32_e32 v144, v144
	v_sub_f32_e32 v143, 1.0, v128
	v_max_f32_e32 v139, 0x800000, v139
	v_log_f32_e32 v139, v139
	v_add_f32_e32 v144, 1.0, v144
	v_rcp_f32_e32 v144, v144
	s_nop 0
	v_fma_f32 v128, v144, v143, v128
	v_mul_f32_e32 v144, 0xbfb8aa3b, v101
	v_exp_f32_e32 v144, v144
	v_sub_f32_e32 v143, 1.0, v145
	v_max_f32_e32 v128, 0x800000, v128
	v_log_f32_e32 v128, v128
	v_add_f32_e32 v144, 1.0, v144
	v_rcp_f32_e32 v144, v144
	s_nop 0
	v_fma_f32 v143, v144, v143, v145
	v_mul_f32_e32 v145, 0xbfb8aa3b, v97
	v_exp_f32_e32 v145, v145
	v_sub_f32_e32 v144, 1.0, v129
	v_max_f32_e32 v143, 0x800000, v143
	v_log_f32_e32 v143, v143
	v_add_f32_e32 v145, 1.0, v145
	v_rcp_f32_e32 v145, v145
	s_nop 0
	v_fma_f32 v129, v145, v144, v129
	v_mul_f32_e32 v145, 0xbfb8aa3b, v102
	v_exp_f32_e32 v145, v145
	v_sub_f32_e32 v144, 1.0, v146
	v_max_f32_e32 v129, 0x800000, v129
	v_log_f32_e32 v129, v129
	v_add_f32_e32 v145, 1.0, v145
	v_rcp_f32_e32 v145, v145
	s_nop 0
	v_fma_f32 v144, v145, v144, v146
	v_mul_f32_e32 v146, 0xbfb8aa3b, v98
	v_exp_f32_e32 v146, v146
	v_sub_f32_e32 v145, 1.0, v130
	v_max_f32_e32 v144, 0x800000, v144
	v_log_f32_e32 v144, v144
	v_add_f32_e32 v146, 1.0, v146
	v_rcp_f32_e32 v146, v146
	s_nop 0
	v_fma_f32 v130, v146, v145, v130
	v_mul_f32_e32 v146, 0xbfb8aa3b, v103
	v_exp_f32_e32 v146, v146
	v_sub_f32_e32 v145, 1.0, v147
	v_max_f32_e32 v130, 0x800000, v130
	v_log_f32_e32 v130, v130
	v_add_f32_e32 v146, 1.0, v146
	v_rcp_f32_e32 v146, v146
	s_nop 0
	v_fmac_f32_e32 v147, v146, v145
	v_max_f32_e32 v145, 0x800000, v147
	v_mul_f32_e32 v147, 0xbfb8aa3b, v99
	v_exp_f32_e32 v147, v147
	v_sub_f32_e32 v146, 1.0, v131
	v_log_f32_e32 v145, v145
	v_add_f32_e32 v147, 1.0, v147
	v_rcp_f32_e32 v147, v147
	s_nop 0
	v_fmac_f32_e32 v131, v147, v146
	v_max_f32_e32 v131, 0x800000, v131
	v_log_f32_e32 v131, v131

; __device__ __forceinline__ float sigm(float x) { return __builtin_amdgcn_rcpf(1.f + __builtin_amdgcn_exp2f(-1.44269504089f * x)); }
;     template <int KIND> __device__ __forceinline__ void seg(unsigned char* w, size_t dst, int ld, int cbase, const float* lb, const pg8::f32x4 (&acc)[2][2][4][2], const pg8::Unit& u, int wr, int wc, int fr, int fq) const {
;     ...
;                         const f32x4 l0 = *(const f32x4*)(lb + c), l1 = *(const f32x4*)(lb + c + 4);
;                         float r[8];
;                         if (lb0) {
; #pragma unroll
;                             for (int i = 0; i < 4; ++i) {
;                                 r[i] = fmaxf(-__log2f(1.f + __builtin_amdgcn_exp2f(-1.44269504089f * lo[i])), -126.f);
;                                 r[4 + i] = fmaxf(-__log2f(1.f + __builtin_amdgcn_exp2f(-1.44269504089f * hi[i])), -126.f);
;                             }
;                         } else {
; #pragma unroll
;                         for (int i = 0; i < 4; ++i) {
;                             const float f0 = l0[i] + (1.f - l0[i]) * sigm(lo[i]); r[i] = __log2f(fmaxf(f0, 1.17549435e-38f));
;                             const float f1 = l1[i] + (1.f - l1[i]) * sigm(hi[i]); r[4 + i] = __log2f(fmaxf(f1, 1.17549435e-38f));
;                         }
.LBB0_600:
	s_andn2_b64 vcc, exec, s[44:45]
	s_cbranch_vccnz .LBB0_602
	s_nop 1
	v_mov_b64_e32 v[128:129], v[168:169]
	v_mov_b64_e32 v[130:131], v[170:171]
	v_mov_b64_e32 v[144:145], v[164:165]
	v_mov_b64_e32 v[146:147], v[166:167]
	v_mul_f32_e32 v140, 0xbfb8aa3b, v92
	v_exp_f32_e32 v140, v140
	v_mul_f32_e32 v141, 0xbfb8aa3b, v88
	v_exp_f32_e32 v141, v141
	v_add_f32_e32 v140, 1.0, v140
	v_rcp_f32_e32 v140, v140
	v_add_f32_e32 v141, 1.0, v141
	v_rcp_f32_e32 v141, v141
	v_sub_f32_e32 v139, 1.0, v144
	v_fma_f32 v139, v140, v139, v144
	v_sub_f32_e32 v140, 1.0, v128
	v_fma_f32 v128, v141, v140, v128
	v_mul_f32_e32 v141, 0xbfb8aa3b, v93
	v_exp_f32_e32 v141, v141
	v_sub_f32_e32 v140, 1.0, v145
	v_max_f32_e32 v139, 0x800000, v139
	v_max_f32_e32 v128, 0x800000, v128
	v_add_f32_e32 v141, 1.0, v141
	v_rcp_f32_e32 v141, v141
	v_log_f32_e32 v139, v139
	v_log_f32_e32 v128, v128
	v_fma_f32 v140, v141, v140, v145
	v_mul_f32_e32 v141, 0xbfb8aa3b, v89
	v_exp_f32_e32 v141, v141
	v_max_f32_e32 v140, 0x800000, v140
	v_log_f32_e32 v143, v140
	v_sub_f32_e32 v140, 1.0, v129
	v_add_f32_e32 v141, 1.0, v141
	v_rcp_f32_e32 v141, v141
	s_nop 0
	v_fma_f32 v129, v141, v140, v129
	v_mul_f32_e32 v141, 0xbfb8aa3b, v94
	v_exp_f32_e32 v141, v141
	v_sub_f32_e32 v140, 1.0, v146
	v_max_f32_e32 v129, 0x800000, v129
	v_log_f32_e32 v129, v129
	v_add_f32_e32 v141, 1.0, v141
	v_rcp_f32_e32 v141, v141
	s_nop 0
	v_fma_f32 v140, v141, v140, v146
	v_mul_f32_e32 v141, 0xbfb8aa3b, v90
	v_exp_f32_e32 v141, v141
	v_max_f32_e32 v140, 0x800000, v140
	v_log_f32_e32 v144, v140
	v_sub_f32_e32 v140, 1.0, v130
	v_add_f32_e32 v141, 1.0, v141
	v_rcp_f32_e32 v141, v141
	s_nop 0
	v_fma_f32 v130, v141, v140, v130
	v_mul_f32_e32 v141, 0xbfb8aa3b, v95
	v_exp_f32_e32 v141, v141
	v_sub_f32_e32 v140, 1.0, v147
	v_max_f32_e32 v130, 0x800000, v130
	v_log_f32_e32 v130, v130
	v_add_f32_e32 v141, 1.0, v141
	v_rcp_f32_e32 v141, v141
	s_nop 0
	v_fmac_f32_e32 v147, v141, v140
	v_mul_f32_e32 v141, 0xbfb8aa3b, v91
	v_exp_f32_e32 v141, v141
	v_max_f32_e32 v140, 0x800000, v147
	v_log_f32_e32 v145, v140
	v_sub_f32_e32 v140, 1.0, v131
	v_add_f32_e32 v141, 1.0, v141
	v_rcp_f32_e32 v141, v141
	s_nop 0
	v_fmac_f32_e32 v131, v141, v140
	v_max_f32_e32 v131, 0x800000, v131
	v_log_f32_e32 v131, v131

; __device__ __forceinline__ float sigm(float x) { return __builtin_amdgcn_rcpf(1.f + __builtin_amdgcn_exp2f(-1.44269504089f * x)); }
;     template <int KIND> __device__ __forceinline__ void seg(unsigned char* w, size_t dst, int ld, int cbase, const float* lb, const pg8::f32x4 (&acc)[2][2][4][2], const pg8::Unit& u, int wr, int wc, int fr, int fq) const {
;     ...
;                         const f32x4 l0 = *(const f32x4*)(lb + c), l1 = *(const f32x4*)(lb + c + 4);
;                         float r[8];
;                         if (lb0) {
; #pragma unroll
;                             for (int i = 0; i < 4; ++i) {
;                                 r[i] = fmaxf(-__log2f(1.f + __builtin_amdgcn_exp2f(-1.44269504089f * lo[i])), -126.f);
;                                 r[4 + i] = fmaxf(-__log2f(1.f + __builtin_amdgcn_exp2f(-1.44269504089f * hi[i])), -126.f);
;                             }
;                         } else {
; #pragma unroll
;                         for (int i = 0; i < 4; ++i) {
;                             const float f0 = l0[i] + (1.f - l0[i]) * sigm(lo[i]); r[i] = __log2f(fmaxf(f0, 1.17549435e-38f));
;                             const float f1 = l1[i] + (1.f - l1[i]) * sigm(hi[i]); r[4 + i] = __log2f(fmaxf(f1, 1.17549435e-38f));
;                         }
.LBB0_604:
	s_andn2_b64 vcc, exec, s[44:45]
	s_cbranch_vccnz .LBB0_606
	s_nop 1
	v_mov_b64_e32 v[128:129], v[176:177]
	v_mov_b64_e32 v[130:131], v[178:179]
	v_mov_b64_e32 v[144:145], v[172:173]
	v_mov_b64_e32 v[146:147], v[174:175]
	v_mul_f32_e32 v143, 0xbfb8aa3b, v84
	v_exp_f32_e32 v143, v143
	v_sub_f32_e32 v139, 1.0, v144
	v_add_f32_e32 v143, 1.0, v143
	v_rcp_f32_e32 v143, v143
	s_nop 0
	v_fma_f32 v139, v143, v139, v144
	v_mul_f32_e32 v144, 0xbfb8aa3b, v80
	v_exp_f32_e32 v144, v144
	v_sub_f32_e32 v143, 1.0, v128
	v_max_f32_e32 v139, 0x800000, v139
	v_log_f32_e32 v139, v139
	v_add_f32_e32 v144, 1.0, v144
	v_rcp_f32_e32 v144, v144
	s_nop 0
	v_fma_f32 v128, v144, v143, v128
	v_mul_f32_e32 v144, 0xbfb8aa3b, v85
	v_exp_f32_e32 v144, v144
	v_sub_f32_e32 v143, 1.0, v145
	v_max_f32_e32 v128, 0x800000, v128
	v_log_f32_e32 v128, v128
	v_add_f32_e32 v144, 1.0, v144
	v_rcp_f32_e32 v144, v144
	s_nop 0
	v_fma_f32 v143, v144, v143, v145
	v_mul_f32_e32 v145, 0xbfb8aa3b, v81
	v_exp_f32_e32 v145, v145
	v_sub_f32_e32 v144, 1.0, v129
	v_max_f32_e32 v143, 0x800000, v143
	v_log_f32_e32 v143, v143
	v_add_f32_e32 v145, 1.0, v145
	v_rcp_f32_e32 v145, v145
	s_nop 0
	v_fma_f32 v129, v145, v144, v129
	v_mul_f32_e32 v145, 0xbfb8aa3b, v86
	v_exp_f32_e32 v145, v145
	v_sub_f32_e32 v144, 1.0, v146
	v_max_f32_e32 v129, 0x800000, v129
	v_log_f32_e32 v129, v129
	v_add_f32_e32 v145, 1.0, v145
	v_rcp_f32_e32 v145, v145
	s_nop 0
	v_fma_f32 v144, v145, v144, v146
	v_mul_f32_e32 v146, 0xbfb8aa3b, v82
	v_exp_f32_e32 v146, v146
	v_sub_f32_e32 v145, 1.0, v130
	v_max_f32_e32 v144, 0x800000, v144
	v_log_f32_e32 v144, v144
	v_add_f32_e32 v146, 1.0, v146
	v_rcp_f32_e32 v146, v146
	s_nop 0
	v_fma_f32 v130, v146, v145, v130
	v_mul_f32_e32 v146, 0xbfb8aa3b, v87
	v_exp_f32_e32 v146, v146
	v_sub_f32_e32 v145, 1.0, v147
	v_max_f32_e32 v130, 0x800000, v130
	v_log_f32_e32 v130, v130
	v_add_f32_e32 v146, 1.0, v146
	v_rcp_f32_e32 v146, v146
	s_nop 0
	v_fmac_f32_e32 v147, v146, v145
	v_max_f32_e32 v145, 0x800000, v147
	v_mul_f32_e32 v147, 0xbfb8aa3b, v83
	v_exp_f32_e32 v147, v147
	v_sub_f32_e32 v146, 1.0, v131
	v_log_f32_e32 v145, v145
	v_add_f32_e32 v147, 1.0, v147
	v_rcp_f32_e32 v147, v147
	s_nop 0
	v_fmac_f32_e32 v131, v147, v146
	v_max_f32_e32 v131, 0x800000, v131
	v_log_f32_e32 v131, v131

; __device__ __forceinline__ float sigm(float x) { return __builtin_amdgcn_rcpf(1.f + __builtin_amdgcn_exp2f(-1.44269504089f * x)); }
;     template <int KIND> __device__ __forceinline__ void seg(unsigned char* w, size_t dst, int ld, int cbase, const float* lb, const pg8::f32x4 (&acc)[2][2][4][2], const pg8::Unit& u, int wr, int wc, int fr, int fq) const {
;     ...
;                         const f32x4 l0 = *(const f32x4*)(lb + c), l1 = *(const f32x4*)(lb + c + 4);
;                         float r[8];
;                         if (lb0) {
; #pragma unroll
;                             for (int i = 0; i < 4; ++i) {
;                                 r[i] = fmaxf(-__log2f(1.f + __builtin_amdgcn_exp2f(-1.44269504089f * lo[i])), -126.f);
;                                 r[4 + i] = fmaxf(-__log2f(1.f + __builtin_amdgcn_exp2f(-1.44269504089f * hi[i])), -126.f);
;                             }
;                         } else {
; #pragma unroll
;                         for (int i = 0; i < 4; ++i) {
;                             const float f0 = l0[i] + (1.f - l0[i]) * sigm(lo[i]); r[i] = __log2f(fmaxf(f0, 1.17549435e-38f));
;                             const float f1 = l1[i] + (1.f - l1[i]) * sigm(hi[i]); r[4 + i] = __log2f(fmaxf(f1, 1.17549435e-38f));
;                         }
.LBB0_608:
	s_andn2_b64 vcc, exec, s[44:45]
	s_cbranch_vccnz .LBB0_610
	s_nop 1
	v_mov_b64_e32 v[128:129], v[168:169]
	v_mov_b64_e32 v[130:131], v[170:171]
	v_mov_b64_e32 v[144:145], v[164:165]
	v_mov_b64_e32 v[146:147], v[166:167]
	v_mul_f32_e32 v140, 0xbfb8aa3b, v76
	v_exp_f32_e32 v140, v140
	v_mul_f32_e32 v141, 0xbfb8aa3b, v72
	v_exp_f32_e32 v141, v141
	v_add_f32_e32 v140, 1.0, v140
	v_rcp_f32_e32 v140, v140
	v_add_f32_e32 v141, 1.0, v141
	v_rcp_f32_e32 v141, v141
	v_sub_f32_e32 v139, 1.0, v144
	v_fma_f32 v139, v140, v139, v144
	v_sub_f32_e32 v140, 1.0, v128
	v_fma_f32 v128, v141, v140, v128
	v_mul_f32_e32 v141, 0xbfb8aa3b, v77
	v_exp_f32_e32 v141, v141
	v_sub_f32_e32 v140, 1.0, v145
	v_max_f32_e32 v139, 0x800000, v139
	v_max_f32_e32 v128, 0x800000, v128
	v_add_f32_e32 v141, 1.0, v141
	v_rcp_f32_e32 v141, v141
	v_log_f32_e32 v139, v139
	v_log_f32_e32 v128, v128
	v_fma_f32 v140, v141, v140, v145
	v_mul_f32_e32 v141, 0xbfb8aa3b, v73
	v_exp_f32_e32 v141, v141
	v_max_f32_e32 v140, 0x800000, v140
	v_log_f32_e32 v143, v140
	v_sub_f32_e32 v140, 1.0, v129
	v_add_f32_e32 v141, 1.0, v141
	v_rcp_f32_e32 v141, v141
	s_nop 0
	v_fma_f32 v129, v141, v140, v129
	v_mul_f32_e32 v141, 0xbfb8aa3b, v78
	v_exp_f32_e32 v141, v141
	v_sub_f32_e32 v140, 1.0, v146
	v_max_f32_e32 v129, 0x800000, v129
	v_log_f32_e32 v129, v129
	v_add_f32_e32 v141, 1.0, v141
	v_rcp_f32_e32 v141, v141
	s_nop 0
	v_fma_f32 v140, v141, v140, v146
	v_mul_f32_e32 v141, 0xbfb8aa3b, v74
	v_exp_f32_e32 v141, v141
	v_max_f32_e32 v140, 0x800000, v140
	v_log_f32_e32 v144, v140
	v_sub_f32_e32 v140, 1.0, v130
	v_add_f32_e32 v141, 1.0, v141
	v_rcp_f32_e32 v141, v141
	s_nop 0
	v_fma_f32 v130, v141, v140, v130
	v_mul_f32_e32 v141, 0xbfb8aa3b, v79
	v_exp_f32_e32 v141, v141
	v_sub_f32_e32 v140, 1.0, v147
	v_max_f32_e32 v130, 0x800000, v130
	v_log_f32_e32 v130, v130
	v_add_f32_e32 v141, 1.0, v141
	v_rcp_f32_e32 v141, v141
	s_nop 0
	v_fmac_f32_e32 v147, v141, v140
	v_mul_f32_e32 v141, 0xbfb8aa3b, v75
	v_exp_f32_e32 v141, v141
	v_max_f32_e32 v140, 0x800000, v147
	v_log_f32_e32 v145, v140
	v_sub_f32_e32 v140, 1.0, v131
	v_add_f32_e32 v141, 1.0, v141
	v_rcp_f32_e32 v141, v141
	s_nop 0
	v_fmac_f32_e32 v131, v141, v140
	v_max_f32_e32 v131, 0x800000, v131
	v_log_f32_e32 v131, v131

; __device__ __forceinline__ float sigm(float x) { return __builtin_amdgcn_rcpf(1.f + __builtin_amdgcn_exp2f(-1.44269504089f * x)); }
;     template <int KIND> __device__ __forceinline__ void seg(unsigned char* w, size_t dst, int ld, int cbase, const float* lb, const pg8::f32x4 (&acc)[2][2][4][2], const pg8::Unit& u, int wr, int wc, int fr, int fq) const {
;     ...
;                         const f32x4 l0 = *(const f32x4*)(lb + c), l1 = *(const f32x4*)(lb + c + 4);
;                         float r[8];
;                         if (lb0) {
; #pragma unroll
;                             for (int i = 0; i < 4; ++i) {
;                                 r[i] = fmaxf(-__log2f(1.f + __builtin_amdgcn_exp2f(-1.44269504089f * lo[i])), -126.f);
;                                 r[4 + i] = fmaxf(-__log2f(1.f + __builtin_amdgcn_exp2f(-1.44269504089f * hi[i])), -126.f);
;                             }
;                         } else {
; #pragma unroll
;                         for (int i = 0; i < 4; ++i) {
;                             const float f0 = l0[i] + (1.f - l0[i]) * sigm(lo[i]); r[i] = __log2f(fmaxf(f0, 1.17549435e-38f));
;                             const float f1 = l1[i] + (1.f - l1[i]) * sigm(hi[i]); r[4 + i] = __log2f(fmaxf(f1, 1.17549435e-38f));
;                         }
.LBB0_612:
	s_andn2_b64 vcc, exec, s[44:45]
	s_cbranch_vccnz .LBB0_614
	s_nop 1
	v_mov_b64_e32 v[128:129], v[176:177]
	v_mov_b64_e32 v[130:131], v[178:179]
	v_mov_b64_e32 v[142:143], v[172:173]
	v_mov_b64_e32 v[144:145], v[174:175]
	v_mul_f32_e32 v146, 0xbfb8aa3b, v68
	v_exp_f32_e32 v146, v146
	v_sub_f32_e32 v139, 1.0, v142
	v_add_f32_e32 v146, 1.0, v146
	v_rcp_f32_e32 v146, v146
	s_nop 0
	v_fma_f32 v139, v146, v139, v142
	v_mul_f32_e32 v146, 0xbfb8aa3b, v64
	v_exp_f32_e32 v146, v146
	v_sub_f32_e32 v142, 1.0, v128
	v_max_f32_e32 v139, 0x800000, v139
	v_log_f32_e32 v139, v139
	v_add_f32_e32 v146, 1.0, v146
	v_rcp_f32_e32 v146, v146
	s_nop 0
	v_fma_f32 v128, v146, v142, v128
	v_mul_f32_e32 v146, 0xbfb8aa3b, v69
	v_exp_f32_e32 v146, v146
	v_sub_f32_e32 v142, 1.0, v143
	v_max_f32_e32 v128, 0x800000, v128
	v_log_f32_e32 v128, v128
	v_add_f32_e32 v146, 1.0, v146
	v_rcp_f32_e32 v146, v146
	s_nop 0
	v_fma_f32 v142, v146, v142, v143
	v_mul_f32_e32 v146, 0xbfb8aa3b, v65
	v_exp_f32_e32 v146, v146
	v_sub_f32_e32 v143, 1.0, v129
	v_max_f32_e32 v142, 0x800000, v142
	v_log_f32_e32 v142, v142
	v_add_f32_e32 v146, 1.0, v146
	v_rcp_f32_e32 v146, v146
	s_nop 0
	v_fma_f32 v129, v146, v143, v129
	v_mul_f32_e32 v146, 0xbfb8aa3b, v70
	v_exp_f32_e32 v146, v146
	v_sub_f32_e32 v143, 1.0, v144
	v_max_f32_e32 v129, 0x800000, v129
	v_log_f32_e32 v129, v129
	v_add_f32_e32 v146, 1.0, v146
	v_rcp_f32_e32 v146, v146
	s_nop 0
	v_fma_f32 v143, v146, v143, v144
	v_mul_f32_e32 v146, 0xbfb8aa3b, v66
	v_exp_f32_e32 v146, v146
	v_sub_f32_e32 v144, 1.0, v130
	v_max_f32_e32 v143, 0x800000, v143
	v_log_f32_e32 v143, v143
	v_add_f32_e32 v146, 1.0, v146
	v_rcp_f32_e32 v146, v146
	s_nop 0
	v_fma_f32 v130, v146, v144, v130
	v_mul_f32_e32 v146, 0xbfb8aa3b, v71
	v_exp_f32_e32 v146, v146
	v_sub_f32_e32 v144, 1.0, v145
	v_max_f32_e32 v130, 0x800000, v130
	v_log_f32_e32 v130, v130
	v_add_f32_e32 v146, 1.0, v146
	v_rcp_f32_e32 v146, v146
	s_nop 0
	v_fmac_f32_e32 v145, v146, v144
	v_mul_f32_e32 v146, 0xbfb8aa3b, v67
	v_exp_f32_e32 v146, v146
	v_max_f32_e32 v144, 0x800000, v145
	v_sub_f32_e32 v145, 1.0, v131
	v_log_f32_e32 v144, v144
	v_add_f32_e32 v146, 1.0, v146
	v_rcp_f32_e32 v146, v146
	s_nop 0
	v_fmac_f32_e32 v131, v146, v145
	v_max_f32_e32 v131, 0x800000, v131
	v_log_f32_e32 v131, v131

; __device__ __forceinline__ float sigm(float x) { return __builtin_amdgcn_rcpf(1.f + __builtin_amdgcn_exp2f(-1.44269504089f * x)); }
;     template <int KIND> __device__ __forceinline__ void seg(unsigned char* w, size_t dst, int ld, int cbase, const float* lb, const pg8::f32x4 (&acc)[2][2][4][2], const pg8::Unit& u, int wr, int wc, int fr, int fq) const {
;     ...
;                         const f32x4 l0 = *(const f32x4*)(lb + c), l1 = *(const f32x4*)(lb + c + 4);
;                         float r[8];
;                         if (lb0) {
; #pragma unroll
;                             for (int i = 0; i < 4; ++i) {
;                                 r[i] = fmaxf(-__log2f(1.f + __builtin_amdgcn_exp2f(-1.44269504089f * lo[i])), -126.f);
;                                 r[4 + i] = fmaxf(-__log2f(1.f + __builtin_amdgcn_exp2f(-1.44269504089f * hi[i])), -126.f);
;                             }
;                         } else {
; #pragma unroll
;                         for (int i = 0; i < 4; ++i) {
;                             const float f0 = l0[i] + (1.f - l0[i]) * sigm(lo[i]); r[i] = __log2f(fmaxf(f0, 1.17549435e-38f));
;                             const float f1 = l1[i] + (1.f - l1[i]) * sigm(hi[i]); r[4 + i] = __log2f(fmaxf(f1, 1.17549435e-38f));
;                         }
.LBB0_616:
	s_andn2_b64 vcc, exec, s[44:45]
	s_cbranch_vccnz .LBB0_618
	s_nop 1
	v_mov_b64_e32 v[128:129], v[168:169]
	v_mov_b64_e32 v[130:131], v[170:171]
	v_mov_b64_e32 v[142:143], v[164:165]
	v_mov_b64_e32 v[144:145], v[166:167]
	v_mul_f32_e32 v140, 0xbfb8aa3b, v60
	v_exp_f32_e32 v140, v140
	v_mul_f32_e32 v141, 0xbfb8aa3b, v56
	v_exp_f32_e32 v141, v141
	v_add_f32_e32 v140, 1.0, v140
	v_rcp_f32_e32 v140, v140
	v_add_f32_e32 v141, 1.0, v141
	v_rcp_f32_e32 v141, v141
	v_sub_f32_e32 v139, 1.0, v142
	v_fma_f32 v139, v140, v139, v142
	v_sub_f32_e32 v140, 1.0, v128
	v_fma_f32 v128, v141, v140, v128
	v_mul_f32_e32 v141, 0xbfb8aa3b, v61
	v_exp_f32_e32 v141, v141
	v_sub_f32_e32 v140, 1.0, v143
	v_max_f32_e32 v139, 0x800000, v139
	v_max_f32_e32 v128, 0x800000, v128
	v_add_f32_e32 v141, 1.0, v141
	v_rcp_f32_e32 v141, v141
	v_log_f32_e32 v139, v139
	v_log_f32_e32 v128, v128
	v_fma_f32 v140, v141, v140, v143
	v_mul_f32_e32 v141, 0xbfb8aa3b, v57
	v_exp_f32_e32 v141, v141
	v_max_f32_e32 v140, 0x800000, v140
	v_log_f32_e32 v142, v140
	v_sub_f32_e32 v140, 1.0, v129
	v_add_f32_e32 v141, 1.0, v141
	v_rcp_f32_e32 v141, v141
	s_nop 0
	v_fma_f32 v129, v141, v140, v129
	v_mul_f32_e32 v141, 0xbfb8aa3b, v62
	v_exp_f32_e32 v141, v141
	v_sub_f32_e32 v140, 1.0, v144
	v_max_f32_e32 v129, 0x800000, v129
	v_log_f32_e32 v129, v129
	v_add_f32_e32 v141, 1.0, v141
	v_rcp_f32_e32 v141, v141
	s_nop 0
	v_fma_f32 v140, v141, v140, v144
	v_mul_f32_e32 v141, 0xbfb8aa3b, v58
	v_exp_f32_e32 v141, v141
	v_max_f32_e32 v140, 0x800000, v140
	v_log_f32_e32 v143, v140
	v_sub_f32_e32 v140, 1.0, v130
	v_add_f32_e32 v141, 1.0, v141
	v_rcp_f32_e32 v141, v141
	s_nop 0
	v_fma_f32 v130, v141, v140, v130
	v_mul_f32_e32 v141, 0xbfb8aa3b, v63
	v_exp_f32_e32 v141, v141
	v_sub_f32_e32 v140, 1.0, v145
	v_max_f32_e32 v130, 0x800000, v130
	v_log_f32_e32 v130, v130
	v_add_f32_e32 v141, 1.0, v141
	v_rcp_f32_e32 v141, v141
	s_nop 0
	v_fmac_f32_e32 v145, v141, v140
	v_mul_f32_e32 v141, 0xbfb8aa3b, v59
	v_exp_f32_e32 v141, v141
	v_max_f32_e32 v140, 0x800000, v145
	v_log_f32_e32 v144, v140
	v_sub_f32_e32 v140, 1.0, v131
	v_add_f32_e32 v141, 1.0, v141
	v_rcp_f32_e32 v141, v141
	s_nop 0
	v_fmac_f32_e32 v131, v141, v140
	v_max_f32_e32 v131, 0x800000, v131
	v_log_f32_e32 v131, v131

; __device__ __forceinline__ float sigm(float x) { return __builtin_amdgcn_rcpf(1.f + __builtin_amdgcn_exp2f(-1.44269504089f * x)); }
;     template <int KIND> __device__ __forceinline__ void seg(unsigned char* w, size_t dst, int ld, int cbase, const float* lb, const pg8::f32x4 (&acc)[2][2][4][2], const pg8::Unit& u, int wr, int wc, int fr, int fq) const {
;     ...
;                         const f32x4 l0 = *(const f32x4*)(lb + c), l1 = *(const f32x4*)(lb + c + 4);
;                         float r[8];
;                         if (lb0) {
; #pragma unroll
;                             for (int i = 0; i < 4; ++i) {
;                                 r[i] = fmaxf(-__log2f(1.f + __builtin_amdgcn_exp2f(-1.44269504089f * lo[i])), -126.f);
;                                 r[4 + i] = fmaxf(-__log2f(1.f + __builtin_amdgcn_exp2f(-1.44269504089f * hi[i])), -126.f);
;                             }
;                         } else {
; #pragma unroll
;                         for (int i = 0; i < 4; ++i) {
;                             const float f0 = l0[i] + (1.f - l0[i]) * sigm(lo[i]); r[i] = __log2f(fmaxf(f0, 1.17549435e-38f));
;                             const float f1 = l1[i] + (1.f - l1[i]) * sigm(hi[i]); r[4 + i] = __log2f(fmaxf(f1, 1.17549435e-38f));
;                         }
.LBB0_620:
	s_andn2_b64 vcc, exec, s[44:45]
	s_cbranch_vccnz .LBB0_622
	s_nop 1
	v_mov_b64_e32 v[128:129], v[176:177]
	v_mov_b64_e32 v[130:131], v[178:179]
	v_mov_b64_e32 v[142:143], v[172:173]
	v_mov_b64_e32 v[144:145], v[174:175]
	v_mul_f32_e32 v146, 0xbfb8aa3b, v52
	v_exp_f32_e32 v146, v146
	v_sub_f32_e32 v139, 1.0, v142
	v_add_f32_e32 v146, 1.0, v146
	v_rcp_f32_e32 v146, v146
	s_nop 0
	v_fma_f32 v139, v146, v139, v142
	v_mul_f32_e32 v146, 0xbfb8aa3b, v48
	v_exp_f32_e32 v146, v146
	v_sub_f32_e32 v142, 1.0, v128
	v_max_f32_e32 v139, 0x800000, v139
	v_log_f32_e32 v139, v139
	v_add_f32_e32 v146, 1.0, v146
	v_rcp_f32_e32 v146, v146
	s_nop 0
	v_fma_f32 v128, v146, v142, v128
	v_mul_f32_e32 v146, 0xbfb8aa3b, v53
	v_exp_f32_e32 v146, v146
	v_sub_f32_e32 v142, 1.0, v143
	v_max_f32_e32 v128, 0x800000, v128
	v_log_f32_e32 v128, v128
	v_add_f32_e32 v146, 1.0, v146
	v_rcp_f32_e32 v146, v146
	s_nop 0
	v_fma_f32 v142, v146, v142, v143
	v_mul_f32_e32 v146, 0xbfb8aa3b, v49
	v_exp_f32_e32 v146, v146
	v_sub_f32_e32 v143, 1.0, v129
	v_max_f32_e32 v142, 0x800000, v142
	v_log_f32_e32 v142, v142
	v_add_f32_e32 v146, 1.0, v146
	v_rcp_f32_e32 v146, v146
	s_nop 0
	v_fma_f32 v129, v146, v143, v129
	v_mul_f32_e32 v146, 0xbfb8aa3b, v54
	v_exp_f32_e32 v146, v146
	v_sub_f32_e32 v143, 1.0, v144
	v_max_f32_e32 v129, 0x800000, v129
	v_log_f32_e32 v129, v129
	v_add_f32_e32 v146, 1.0, v146
	v_rcp_f32_e32 v146, v146
	s_nop 0
	v_fma_f32 v143, v146, v143, v144
	v_mul_f32_e32 v146, 0xbfb8aa3b, v50
	v_exp_f32_e32 v146, v146
	v_sub_f32_e32 v144, 1.0, v130
	v_max_f32_e32 v143, 0x800000, v143
	v_log_f32_e32 v143, v143
	v_add_f32_e32 v146, 1.0, v146
	v_rcp_f32_e32 v146, v146
	s_nop 0
	v_fma_f32 v130, v146, v144, v130
	v_mul_f32_e32 v146, 0xbfb8aa3b, v55
	v_exp_f32_e32 v146, v146
	v_sub_f32_e32 v144, 1.0, v145
	v_max_f32_e32 v130, 0x800000, v130
	v_log_f32_e32 v130, v130
	v_add_f32_e32 v146, 1.0, v146
	v_rcp_f32_e32 v146, v146
	s_nop 0
	v_fmac_f32_e32 v145, v146, v144
	v_mul_f32_e32 v146, 0xbfb8aa3b, v51
	v_exp_f32_e32 v146, v146
	v_max_f32_e32 v144, 0x800000, v145
	v_sub_f32_e32 v145, 1.0, v131
	v_log_f32_e32 v144, v144
	v_add_f32_e32 v146, 1.0, v146
	v_rcp_f32_e32 v146, v146
	s_nop 0
	v_fmac_f32_e32 v131, v146, v145
	v_max_f32_e32 v131, 0x800000, v131
	v_log_f32_e32 v131, v131

; __device__ __forceinline__ float sigm(float x) { return __builtin_amdgcn_rcpf(1.f + __builtin_amdgcn_exp2f(-1.44269504089f * x)); }
;     template <int KIND> __device__ __forceinline__ void seg(unsigned char* w, size_t dst, int ld, int cbase, const float* lb, const pg8::f32x4 (&acc)[2][2][4][2], const pg8::Unit& u, int wr, int wc, int fr, int fq) const {
;     ...
;                         const f32x4 l0 = *(const f32x4*)(lb + c), l1 = *(const f32x4*)(lb + c + 4);
;                         float r[8];
;                         if (lb0) {
; #pragma unroll
;                             for (int i = 0; i < 4; ++i) {
;                                 r[i] = fmaxf(-__log2f(1.f + __builtin_amdgcn_exp2f(-1.44269504089f * lo[i])), -126.f);
;                                 r[4 + i] = fmaxf(-__log2f(1.f + __builtin_amdgcn_exp2f(-1.44269504089f * hi[i])), -126.f);
;                             }
;                         } else {
; #pragma unroll
;                         for (int i = 0; i < 4; ++i) {
;                             const float f0 = l0[i] + (1.f - l0[i]) * sigm(lo[i]); r[i] = __log2f(fmaxf(f0, 1.17549435e-38f));
;                             const float f1 = l1[i] + (1.f - l1[i]) * sigm(hi[i]); r[4 + i] = __log2f(fmaxf(f1, 1.17549435e-38f));
;                         }
.LBB0_624:
	s_andn2_b64 vcc, exec, s[44:45]
	s_cbranch_vccnz .LBB0_626
	s_nop 1
	v_mov_b64_e32 v[128:129], v[168:169]
	v_mov_b64_e32 v[130:131], v[170:171]
	v_mov_b64_e32 v[142:143], v[164:165]
	v_mov_b64_e32 v[144:145], v[166:167]
	v_mul_f32_e32 v140, 0xbfb8aa3b, v44
	v_exp_f32_e32 v140, v140
	v_mul_f32_e32 v141, 0xbfb8aa3b, v40
	v_exp_f32_e32 v141, v141
	v_add_f32_e32 v140, 1.0, v140
	v_rcp_f32_e32 v140, v140
	v_add_f32_e32 v141, 1.0, v141
	v_rcp_f32_e32 v141, v141
	v_sub_f32_e32 v139, 1.0, v142
	v_fma_f32 v139, v140, v139, v142
	v_sub_f32_e32 v140, 1.0, v128
	v_fma_f32 v128, v141, v140, v128
	v_mul_f32_e32 v141, 0xbfb8aa3b, v45
	v_exp_f32_e32 v141, v141
	v_sub_f32_e32 v140, 1.0, v143
	v_max_f32_e32 v139, 0x800000, v139
	v_max_f32_e32 v128, 0x800000, v128
	v_add_f32_e32 v141, 1.0, v141
	v_rcp_f32_e32 v141, v141
	v_log_f32_e32 v139, v139
	v_log_f32_e32 v128, v128
	v_fma_f32 v140, v141, v140, v143
	v_mul_f32_e32 v141, 0xbfb8aa3b, v41
	v_exp_f32_e32 v141, v141
	v_max_f32_e32 v140, 0x800000, v140
	v_log_f32_e32 v142, v140
	v_sub_f32_e32 v140, 1.0, v129
	v_add_f32_e32 v141, 1.0, v141
	v_rcp_f32_e32 v141, v141
	s_nop 0
	v_fma_f32 v129, v141, v140, v129
	v_mul_f32_e32 v141, 0xbfb8aa3b, v46
	v_exp_f32_e32 v141, v141
	v_sub_f32_e32 v140, 1.0, v144
	v_max_f32_e32 v129, 0x800000, v129
	v_log_f32_e32 v129, v129
	v_add_f32_e32 v141, 1.0, v141
	v_rcp_f32_e32 v141, v141
	s_nop 0
	v_fma_f32 v140, v141, v140, v144
	v_mul_f32_e32 v141, 0xbfb8aa3b, v42
	v_exp_f32_e32 v141, v141
	v_max_f32_e32 v140, 0x800000, v140
	v_log_f32_e32 v143, v140
	v_sub_f32_e32 v140, 1.0, v130
	v_add_f32_e32 v141, 1.0, v141
	v_rcp_f32_e32 v141, v141
	s_nop 0
	v_fma_f32 v130, v141, v140, v130
	v_mul_f32_e32 v141, 0xbfb8aa3b, v47
	v_exp_f32_e32 v141, v141
	v_sub_f32_e32 v140, 1.0, v145
	v_max_f32_e32 v130, 0x800000, v130
	v_log_f32_e32 v130, v130
	v_add_f32_e32 v141, 1.0, v141
	v_rcp_f32_e32 v141, v141
	s_nop 0
	v_fmac_f32_e32 v145, v141, v140
	v_mul_f32_e32 v141, 0xbfb8aa3b, v43
	v_exp_f32_e32 v141, v141
	v_max_f32_e32 v140, 0x800000, v145
	v_log_f32_e32 v144, v140
	v_sub_f32_e32 v140, 1.0, v131
	v_add_f32_e32 v141, 1.0, v141
	v_rcp_f32_e32 v141, v141
	s_nop 0
	v_fmac_f32_e32 v131, v141, v140
	v_max_f32_e32 v131, 0x800000, v131
	v_log_f32_e32 v131, v131

; __device__ __forceinline__ float sigm(float x) { return __builtin_amdgcn_rcpf(1.f + __builtin_amdgcn_exp2f(-1.44269504089f * x)); }
;     template <int KIND> __device__ __forceinline__ void seg(unsigned char* w, size_t dst, int ld, int cbase, const float* lb, const pg8::f32x4 (&acc)[2][2][4][2], const pg8::Unit& u, int wr, int wc, int fr, int fq) const {
;     ...
;                         const f32x4 l0 = *(const f32x4*)(lb + c), l1 = *(const f32x4*)(lb + c + 4);
;                         float r[8];
;                         if (lb0) {
; #pragma unroll
;                             for (int i = 0; i < 4; ++i) {
;                                 r[i] = fmaxf(-__log2f(1.f + __builtin_amdgcn_exp2f(-1.44269504089f * lo[i])), -126.f);
;                                 r[4 + i] = fmaxf(-__log2f(1.f + __builtin_amdgcn_exp2f(-1.44269504089f * hi[i])), -126.f);
;                             }
;                         } else {
; #pragma unroll
;                         for (int i = 0; i < 4; ++i) {
;                             const float f0 = l0[i] + (1.f - l0[i]) * sigm(lo[i]); r[i] = __log2f(fmaxf(f0, 1.17549435e-38f));
;                             const float f1 = l1[i] + (1.f - l1[i]) * sigm(hi[i]); r[4 + i] = __log2f(fmaxf(f1, 1.17549435e-38f));
;                         }
.LBB0_628:
	s_andn2_b64 vcc, exec, s[44:45]
	s_cbranch_vccnz .LBB0_630
	s_nop 1
	v_mov_b64_e32 v[128:129], v[176:177]
	v_mov_b64_e32 v[130:131], v[178:179]
	v_mov_b64_e32 v[142:143], v[172:173]
	v_mov_b64_e32 v[144:145], v[174:175]
	v_mul_f32_e32 v146, 0xbfb8aa3b, v36
	v_exp_f32_e32 v146, v146
	v_sub_f32_e32 v139, 1.0, v142
	v_add_f32_e32 v146, 1.0, v146
	v_rcp_f32_e32 v146, v146
	s_nop 0
	v_fma_f32 v139, v146, v139, v142
	v_mul_f32_e32 v146, 0xbfb8aa3b, v32
	v_exp_f32_e32 v146, v146
	v_sub_f32_e32 v142, 1.0, v128
	v_max_f32_e32 v139, 0x800000, v139
	v_log_f32_e32 v139, v139
	v_add_f32_e32 v146, 1.0, v146
	v_rcp_f32_e32 v146, v146
	s_nop 0
	v_fma_f32 v128, v146, v142, v128
	v_mul_f32_e32 v146, 0xbfb8aa3b, v37
	v_exp_f32_e32 v146, v146
	v_sub_f32_e32 v142, 1.0, v143
	v_max_f32_e32 v128, 0x800000, v128
	v_log_f32_e32 v128, v128
	v_add_f32_e32 v146, 1.0, v146
	v_rcp_f32_e32 v146, v146
	s_nop 0
	v_fma_f32 v142, v146, v142, v143
	v_mul_f32_e32 v146, 0xbfb8aa3b, v33
	v_exp_f32_e32 v146, v146
	v_sub_f32_e32 v143, 1.0, v129
	v_max_f32_e32 v142, 0x800000, v142
	v_log_f32_e32 v142, v142
	v_add_f32_e32 v146, 1.0, v146
	v_rcp_f32_e32 v146, v146
	s_nop 0
	v_fma_f32 v129, v146, v143, v129
	v_mul_f32_e32 v146, 0xbfb8aa3b, v38
	v_exp_f32_e32 v146, v146
	v_sub_f32_e32 v143, 1.0, v144
	v_max_f32_e32 v129, 0x800000, v129
	v_log_f32_e32 v129, v129
	v_add_f32_e32 v146, 1.0, v146
	v_rcp_f32_e32 v146, v146
	s_nop 0
	v_fma_f32 v143, v146, v143, v144
	v_mul_f32_e32 v146, 0xbfb8aa3b, v34
	v_exp_f32_e32 v146, v146
	v_sub_f32_e32 v144, 1.0, v130
	v_max_f32_e32 v143, 0x800000, v143
	v_log_f32_e32 v143, v143
	v_add_f32_e32 v146, 1.0, v146
	v_rcp_f32_e32 v146, v146
	s_nop 0
	v_fma_f32 v130, v146, v144, v130
	v_mul_f32_e32 v146, 0xbfb8aa3b, v39
	v_exp_f32_e32 v146, v146
	v_sub_f32_e32 v144, 1.0, v145
	v_max_f32_e32 v130, 0x800000, v130
	v_log_f32_e32 v130, v130
	v_add_f32_e32 v146, 1.0, v146
	v_rcp_f32_e32 v146, v146
	s_nop 0
	v_fmac_f32_e32 v145, v146, v144
	v_mul_f32_e32 v146, 0xbfb8aa3b, v35
	v_exp_f32_e32 v146, v146
	v_max_f32_e32 v144, 0x800000, v145
	v_sub_f32_e32 v145, 1.0, v131
	v_log_f32_e32 v144, v144
	v_add_f32_e32 v146, 1.0, v146
	v_rcp_f32_e32 v146, v146
	s_nop 0
	v_fmac_f32_e32 v131, v146, v145
	v_max_f32_e32 v131, 0x800000, v131
	v_log_f32_e32 v131, v131

; __device__ __forceinline__ float sigm(float x) { return __builtin_amdgcn_rcpf(1.f + __builtin_amdgcn_exp2f(-1.44269504089f * x)); }
;     template <int KIND> __device__ __forceinline__ void seg(unsigned char* w, size_t dst, int ld, int cbase, const float* lb, const pg8::f32x4 (&acc)[2][2][4][2], const pg8::Unit& u, int wr, int wc, int fr, int fq) const {
;     ...
;                         const f32x4 l0 = *(const f32x4*)(lb + c), l1 = *(const f32x4*)(lb + c + 4);
;                         float r[8];
;                         if (lb0) {
; #pragma unroll
;                             for (int i = 0; i < 4; ++i) {
;                                 r[i] = fmaxf(-__log2f(1.f + __builtin_amdgcn_exp2f(-1.44269504089f * lo[i])), -126.f);
;                                 r[4 + i] = fmaxf(-__log2f(1.f + __builtin_amdgcn_exp2f(-1.44269504089f * hi[i])), -126.f);
;                             }
;                         } else {
; #pragma unroll
;                         for (int i = 0; i < 4; ++i) {
;                             const float f0 = l0[i] + (1.f - l0[i]) * sigm(lo[i]); r[i] = __log2f(fmaxf(f0, 1.17549435e-38f));
;                             const float f1 = l1[i] + (1.f - l1[i]) * sigm(hi[i]); r[4 + i] = __log2f(fmaxf(f1, 1.17549435e-38f));
;                         }
.LBB0_632:
	s_andn2_b64 vcc, exec, s[44:45]
	s_cbranch_vccnz .LBB0_634
	s_nop 1
	v_mov_b64_e32 v[128:129], v[168:169]
	v_mov_b64_e32 v[130:131], v[170:171]
	v_mov_b64_e32 v[142:143], v[164:165]
	v_mov_b64_e32 v[144:145], v[166:167]
	v_mul_f32_e32 v140, 0xbfb8aa3b, v28
	v_exp_f32_e32 v140, v140
	v_mul_f32_e32 v141, 0xbfb8aa3b, v24
	v_exp_f32_e32 v141, v141
	v_add_f32_e32 v140, 1.0, v140
	v_rcp_f32_e32 v140, v140
	v_add_f32_e32 v141, 1.0, v141
	v_rcp_f32_e32 v141, v141
	v_sub_f32_e32 v139, 1.0, v142
	v_fma_f32 v139, v140, v139, v142
	v_sub_f32_e32 v140, 1.0, v128
	v_fma_f32 v128, v141, v140, v128
	v_mul_f32_e32 v141, 0xbfb8aa3b, v29
	v_exp_f32_e32 v141, v141
	v_sub_f32_e32 v140, 1.0, v143
	v_max_f32_e32 v139, 0x800000, v139
	v_max_f32_e32 v128, 0x800000, v128
	v_add_f32_e32 v141, 1.0, v141
	v_rcp_f32_e32 v141, v141
	v_log_f32_e32 v139, v139
	v_log_f32_e32 v128, v128
	v_fma_f32 v140, v141, v140, v143
	v_mul_f32_e32 v141, 0xbfb8aa3b, v25
	v_exp_f32_e32 v141, v141
	v_max_f32_e32 v140, 0x800000, v140
	v_log_f32_e32 v142, v140
	v_sub_f32_e32 v140, 1.0, v129
	v_add_f32_e32 v141, 1.0, v141
	v_rcp_f32_e32 v141, v141
	s_nop 0
	v_fma_f32 v129, v141, v140, v129
	v_mul_f32_e32 v141, 0xbfb8aa3b, v30
	v_exp_f32_e32 v141, v141
	v_sub_f32_e32 v140, 1.0, v144
	v_max_f32_e32 v129, 0x800000, v129
	v_log_f32_e32 v129, v129
	v_add_f32_e32 v141, 1.0, v141
	v_rcp_f32_e32 v141, v141
	s_nop 0
	v_fma_f32 v140, v141, v140, v144
	v_mul_f32_e32 v141, 0xbfb8aa3b, v26
	v_exp_f32_e32 v141, v141
	v_max_f32_e32 v140, 0x800000, v140
	v_log_f32_e32 v143, v140
	v_sub_f32_e32 v140, 1.0, v130
	v_add_f32_e32 v141, 1.0, v141
	v_rcp_f32_e32 v141, v141
	s_nop 0
	v_fma_f32 v130, v141, v140, v130
	v_mul_f32_e32 v141, 0xbfb8aa3b, v31
	v_exp_f32_e32 v141, v141
	v_sub_f32_e32 v140, 1.0, v145
	v_max_f32_e32 v130, 0x800000, v130
	v_log_f32_e32 v130, v130
	v_add_f32_e32 v141, 1.0, v141
	v_rcp_f32_e32 v141, v141
	s_nop 0
	v_fmac_f32_e32 v145, v141, v140
	v_mul_f32_e32 v141, 0xbfb8aa3b, v27
	v_exp_f32_e32 v141, v141
	v_max_f32_e32 v140, 0x800000, v145
	v_log_f32_e32 v144, v140
	v_sub_f32_e32 v140, 1.0, v131
	v_add_f32_e32 v141, 1.0, v141
	v_rcp_f32_e32 v141, v141
	s_nop 0
	v_fmac_f32_e32 v131, v141, v140
	v_max_f32_e32 v131, 0x800000, v131
	v_log_f32_e32 v131, v131

; __device__ __forceinline__ float sigm(float x) { return __builtin_amdgcn_rcpf(1.f + __builtin_amdgcn_exp2f(-1.44269504089f * x)); }
;     template <int KIND> __device__ __forceinline__ void seg(unsigned char* w, size_t dst, int ld, int cbase, const float* lb, const pg8::f32x4 (&acc)[2][2][4][2], const pg8::Unit& u, int wr, int wc, int fr, int fq) const {
;     ...
;                         const f32x4 l0 = *(const f32x4*)(lb + c), l1 = *(const f32x4*)(lb + c + 4);
;                         float r[8];
;                         if (lb0) {
; #pragma unroll
;                             for (int i = 0; i < 4; ++i) {
;                                 r[i] = fmaxf(-__log2f(1.f + __builtin_amdgcn_exp2f(-1.44269504089f * lo[i])), -126.f);
;                                 r[4 + i] = fmaxf(-__log2f(1.f + __builtin_amdgcn_exp2f(-1.44269504089f * hi[i])), -126.f);
;                             }
;                         } else {
; #pragma unroll
;                         for (int i = 0; i < 4; ++i) {
;                             const float f0 = l0[i] + (1.f - l0[i]) * sigm(lo[i]); r[i] = __log2f(fmaxf(f0, 1.17549435e-38f));
;                             const float f1 = l1[i] + (1.f - l1[i]) * sigm(hi[i]); r[4 + i] = __log2f(fmaxf(f1, 1.17549435e-38f));
;                         }
.LBB0_636:
	s_andn2_b64 vcc, exec, s[44:45]
	s_cbranch_vccnz .LBB0_638
	s_nop 1
	v_mov_b64_e32 v[128:129], v[176:177]
	v_mov_b64_e32 v[130:131], v[178:179]
	v_mov_b64_e32 v[142:143], v[172:173]
	v_mov_b64_e32 v[144:145], v[174:175]
	v_mul_f32_e32 v146, 0xbfb8aa3b, v20
	v_exp_f32_e32 v146, v146
	v_sub_f32_e32 v139, 1.0, v142
	v_add_f32_e32 v146, 1.0, v146
	v_rcp_f32_e32 v146, v146
	s_nop 0
	v_fma_f32 v139, v146, v139, v142
	v_mul_f32_e32 v146, 0xbfb8aa3b, v16
	v_exp_f32_e32 v146, v146
	v_sub_f32_e32 v142, 1.0, v128
	v_max_f32_e32 v139, 0x800000, v139
	v_log_f32_e32 v139, v139
	v_add_f32_e32 v146, 1.0, v146
	v_rcp_f32_e32 v146, v146
	s_nop 0
	v_fma_f32 v128, v146, v142, v128
	v_mul_f32_e32 v146, 0xbfb8aa3b, v21
	v_exp_f32_e32 v146, v146
	v_sub_f32_e32 v142, 1.0, v143
	v_max_f32_e32 v128, 0x800000, v128
	v_log_f32_e32 v128, v128
	v_add_f32_e32 v146, 1.0, v146
	v_rcp_f32_e32 v146, v146
	s_nop 0
	v_fma_f32 v142, v146, v142, v143
	v_mul_f32_e32 v146, 0xbfb8aa3b, v17
	v_exp_f32_e32 v146, v146
	v_sub_f32_e32 v143, 1.0, v129
	v_max_f32_e32 v142, 0x800000, v142
	v_log_f32_e32 v142, v142
	v_add_f32_e32 v146, 1.0, v146
	v_rcp_f32_e32 v146, v146
	s_nop 0
	v_fma_f32 v129, v146, v143, v129
	v_mul_f32_e32 v146, 0xbfb8aa3b, v22
	v_exp_f32_e32 v146, v146
	v_sub_f32_e32 v143, 1.0, v144
	v_max_f32_e32 v129, 0x800000, v129
	v_log_f32_e32 v129, v129
	v_add_f32_e32 v146, 1.0, v146
	v_rcp_f32_e32 v146, v146
	s_nop 0
	v_fma_f32 v143, v146, v143, v144
	v_mul_f32_e32 v146, 0xbfb8aa3b, v18
	v_exp_f32_e32 v146, v146
	v_sub_f32_e32 v144, 1.0, v130
	v_max_f32_e32 v143, 0x800000, v143
	v_log_f32_e32 v143, v143
	v_add_f32_e32 v146, 1.0, v146
	v_rcp_f32_e32 v146, v146
	s_nop 0
	v_fma_f32 v130, v146, v144, v130
	v_mul_f32_e32 v146, 0xbfb8aa3b, v23
	v_exp_f32_e32 v146, v146
	v_sub_f32_e32 v144, 1.0, v145
	v_max_f32_e32 v130, 0x800000, v130
	v_log_f32_e32 v130, v130
	v_add_f32_e32 v146, 1.0, v146
	v_rcp_f32_e32 v146, v146
	s_nop 0
	v_fmac_f32_e32 v145, v146, v144
	v_mul_f32_e32 v146, 0xbfb8aa3b, v19
	v_exp_f32_e32 v146, v146
	v_max_f32_e32 v144, 0x800000, v145
	v_sub_f32_e32 v145, 1.0, v131
	v_log_f32_e32 v144, v144
	v_add_f32_e32 v146, 1.0, v146
	v_rcp_f32_e32 v146, v146
	s_nop 0
	v_fmac_f32_e32 v131, v146, v145
	v_max_f32_e32 v131, 0x800000, v131
	v_log_f32_e32 v131, v131

; __device__ __forceinline__ float sigm(float x) { return __builtin_amdgcn_rcpf(1.f + __builtin_amdgcn_exp2f(-1.44269504089f * x)); }
;     template <int KIND> __device__ __forceinline__ void seg(unsigned char* w, size_t dst, int ld, int cbase, const float* lb, const pg8::f32x4 (&acc)[2][2][4][2], const pg8::Unit& u, int wr, int wc, int fr, int fq) const {
;     ...
;                         const f32x4 l0 = *(const f32x4*)(lb + c), l1 = *(const f32x4*)(lb + c + 4);
;                         float r[8];
;                         if (lb0) {
; #pragma unroll
;                             for (int i = 0; i < 4; ++i) {
;                                 r[i] = fmaxf(-__log2f(1.f + __builtin_amdgcn_exp2f(-1.44269504089f * lo[i])), -126.f);
;                                 r[4 + i] = fmaxf(-__log2f(1.f + __builtin_amdgcn_exp2f(-1.44269504089f * hi[i])), -126.f);
;                             }
;                         } else {
; #pragma unroll
;                         for (int i = 0; i < 4; ++i) {
;                             const float f0 = l0[i] + (1.f - l0[i]) * sigm(lo[i]); r[i] = __log2f(fmaxf(f0, 1.17549435e-38f));
;                             const float f1 = l1[i] + (1.f - l1[i]) * sigm(hi[i]); r[4 + i] = __log2f(fmaxf(f1, 1.17549435e-38f));
;                         }
.LBB0_640:
	s_andn2_b64 vcc, exec, s[44:45]
	s_cbranch_vccnz .LBB0_642
	s_nop 1
	v_mov_b64_e32 v[128:129], v[168:169]
	v_mov_b64_e32 v[130:131], v[170:171]
	v_mov_b64_e32 v[140:141], v[164:165]
	v_mov_b64_e32 v[142:143], v[166:167]
	v_mul_f32_e32 v135, 0xbfb8aa3b, v12
	v_exp_f32_e32 v135, v135
	v_sub_f32_e32 v134, 1.0, v140
	v_add_f32_e32 v135, 1.0, v135
	v_rcp_f32_e32 v135, v135
	s_nop 0
	v_fma_f32 v134, v135, v134, v140
	v_mul_f32_e32 v135, 0xbfb8aa3b, v8
	v_exp_f32_e32 v135, v135
	v_max_f32_e32 v134, 0x800000, v134
	v_log_f32_e32 v139, v134
	v_sub_f32_e32 v134, 1.0, v128
	v_add_f32_e32 v135, 1.0, v135
	v_rcp_f32_e32 v135, v135
	s_nop 0
	v_fma_f32 v128, v135, v134, v128
	v_mul_f32_e32 v135, 0xbfb8aa3b, v13
	v_exp_f32_e32 v135, v135
	v_sub_f32_e32 v134, 1.0, v141
	v_max_f32_e32 v128, 0x800000, v128
	v_log_f32_e32 v128, v128
	v_add_f32_e32 v135, 1.0, v135
	v_rcp_f32_e32 v135, v135
	s_nop 0
	v_fma_f32 v134, v135, v134, v141
	v_mul_f32_e32 v135, 0xbfb8aa3b, v9
	v_exp_f32_e32 v135, v135
	v_max_f32_e32 v134, 0x800000, v134
	v_log_f32_e32 v140, v134
	v_sub_f32_e32 v134, 1.0, v129
	v_add_f32_e32 v135, 1.0, v135
	v_rcp_f32_e32 v135, v135
	s_nop 0
	v_fma_f32 v129, v135, v134, v129
	v_mul_f32_e32 v135, 0xbfb8aa3b, v14
	v_exp_f32_e32 v135, v135
	v_sub_f32_e32 v134, 1.0, v142
	v_max_f32_e32 v129, 0x800000, v129
	v_log_f32_e32 v129, v129
	v_add_f32_e32 v135, 1.0, v135
	v_rcp_f32_e32 v135, v135
	s_nop 0
	v_fma_f32 v134, v135, v134, v142
	v_mul_f32_e32 v135, 0xbfb8aa3b, v10
	v_exp_f32_e32 v135, v135
	v_max_f32_e32 v134, 0x800000, v134
	v_log_f32_e32 v141, v134
	v_sub_f32_e32 v134, 1.0, v130
	v_add_f32_e32 v135, 1.0, v135
	v_rcp_f32_e32 v135, v135
	s_nop 0
	v_fma_f32 v130, v135, v134, v130
	v_mul_f32_e32 v135, 0xbfb8aa3b, v15
	v_exp_f32_e32 v135, v135
	v_sub_f32_e32 v134, 1.0, v143
	v_max_f32_e32 v130, 0x800000, v130
	v_log_f32_e32 v130, v130
	v_add_f32_e32 v135, 1.0, v135
	v_rcp_f32_e32 v135, v135
	s_nop 0
	v_fmac_f32_e32 v143, v135, v134
	v_mul_f32_e32 v135, 0xbfb8aa3b, v11
	v_exp_f32_e32 v135, v135
	v_max_f32_e32 v134, 0x800000, v143
	v_log_f32_e32 v142, v134
	v_sub_f32_e32 v134, 1.0, v131
	v_add_f32_e32 v135, 1.0, v135
	v_rcp_f32_e32 v135, v135
	s_nop 0
	v_fmac_f32_e32 v131, v135, v134
	v_max_f32_e32 v131, 0x800000, v131
	v_log_f32_e32 v131, v131

; __device__ __forceinline__ float sigm(float x) { return __builtin_amdgcn_rcpf(1.f + __builtin_amdgcn_exp2f(-1.44269504089f * x)); }
;     template <int KIND> __device__ __forceinline__ void seg(unsigned char* w, size_t dst, int ld, int cbase, const float* lb, const pg8::f32x4 (&acc)[2][2][4][2], const pg8::Unit& u, int wr, int wc, int fr, int fq) const {
;     ...
;                         const f32x4 l0 = *(const f32x4*)(lb + c), l1 = *(const f32x4*)(lb + c + 4);
;                         float r[8];
;                         if (lb0) {
; #pragma unroll
;                             for (int i = 0; i < 4; ++i) {
;                                 r[i] = fmaxf(-__log2f(1.f + __builtin_amdgcn_exp2f(-1.44269504089f * lo[i])), -126.f);
;                                 r[4 + i] = fmaxf(-__log2f(1.f + __builtin_amdgcn_exp2f(-1.44269504089f * hi[i])), -126.f);
;                             }
;                         } else {
; #pragma unroll
;                         for (int i = 0; i < 4; ++i) {
;                             const float f0 = l0[i] + (1.f - l0[i]) * sigm(lo[i]); r[i] = __log2f(fmaxf(f0, 1.17549435e-38f));
;                             const float f1 = l1[i] + (1.f - l1[i]) * sigm(hi[i]); r[4 + i] = __log2f(fmaxf(f1, 1.17549435e-38f));
;                         }
.LBB0_644:
	s_andn2_b64 vcc, exec, s[8:9]
	s_cbranch_vccnz .LBB0_646
	s_nop 1
	v_mov_b64_e32 v[128:129], v[176:177]
	v_mov_b64_e32 v[130:131], v[178:179]
	v_mov_b64_e32 v[138:139], v[172:173]
	v_mov_b64_e32 v[140:141], v[174:175]
	v_mul_f32_e32 v137, 0xbfb8aa3b, v4
	v_exp_f32_e32 v137, v137
	v_sub_f32_e32 v136, 1.0, v138
	v_add_f32_e32 v137, 1.0, v137
	v_rcp_f32_e32 v137, v137
	s_nop 0
	v_fma_f32 v136, v137, v136, v138
	v_mul_f32_e32 v137, 0xbfb8aa3b, v0
	v_exp_f32_e32 v137, v137
	v_max_f32_e32 v136, 0x800000, v136
	v_log_f32_e32 v138, v136
	v_sub_f32_e32 v136, 1.0, v128
	v_add_f32_e32 v137, 1.0, v137
	v_rcp_f32_e32 v137, v137
	s_nop 0
	v_fma_f32 v128, v137, v136, v128
	v_mul_f32_e32 v137, 0xbfb8aa3b, v5
	v_exp_f32_e32 v137, v137
	v_sub_f32_e32 v136, 1.0, v139
	v_max_f32_e32 v128, 0x800000, v128
	v_log_f32_e32 v128, v128
	v_add_f32_e32 v137, 1.0, v137
	v_rcp_f32_e32 v137, v137
	s_nop 0
	v_fma_f32 v136, v137, v136, v139
	v_mul_f32_e32 v137, 0xbfb8aa3b, v1
	v_exp_f32_e32 v137, v137
	v_max_f32_e32 v136, 0x800000, v136
	v_log_f32_e32 v139, v136
	v_sub_f32_e32 v136, 1.0, v129
	v_add_f32_e32 v137, 1.0, v137
	v_rcp_f32_e32 v137, v137
	s_nop 0
	v_fma_f32 v129, v137, v136, v129
	v_mul_f32_e32 v137, 0xbfb8aa3b, v6
	v_exp_f32_e32 v137, v137
	v_sub_f32_e32 v136, 1.0, v140
	v_max_f32_e32 v129, 0x800000, v129
	v_log_f32_e32 v129, v129
	v_add_f32_e32 v137, 1.0, v137
	v_rcp_f32_e32 v137, v137
	s_nop 0
	v_fma_f32 v136, v137, v136, v140
	v_mul_f32_e32 v137, 0xbfb8aa3b, v2
	v_exp_f32_e32 v137, v137
	v_max_f32_e32 v136, 0x800000, v136
	v_log_f32_e32 v140, v136
	v_sub_f32_e32 v136, 1.0, v130
	v_add_f32_e32 v137, 1.0, v137
	v_rcp_f32_e32 v137, v137
	s_nop 0
	v_fma_f32 v130, v137, v136, v130
	v_mul_f32_e32 v137, 0xbfb8aa3b, v7
	v_exp_f32_e32 v137, v137
	v_sub_f32_e32 v136, 1.0, v141
	v_max_f32_e32 v130, 0x800000, v130
	v_log_f32_e32 v130, v130
	v_add_f32_e32 v137, 1.0, v137
	v_rcp_f32_e32 v137, v137
	s_nop 0
	v_fmac_f32_e32 v141, v137, v136
	v_mul_f32_e32 v137, 0xbfb8aa3b, v3
	v_exp_f32_e32 v137, v137
	v_max_f32_e32 v136, 0x800000, v141
	v_log_f32_e32 v141, v136
	v_sub_f32_e32 v136, 1.0, v131
	v_add_f32_e32 v137, 1.0, v137
	v_rcp_f32_e32 v137, v137
	s_nop 0
	v_fmac_f32_e32 v131, v137, v136
	v_max_f32_e32 v131, 0x800000, v131
	v_log_f32_e32 v131, v131
